# P1 peeled first two rows: bpermute butterflies converted in place to DPP/permlane swaps (bit-identical), on sc4
# speedup vs baseline: 1.0013x; 1.0011x over previous
; #define GAS __attribute__((address_space(1)))
; __device__ __forceinline__ float wave_sum(float v) {
; #pragma unroll
;     for (int o = 1; o < 64; o <<= 1) v += __shfl_xor(v, o);
;     return v;
; template <int LO, int HI> __global__ void __launch_bounds__(NWAVES * 64, 2) fox_fwd(Args args) {
;     ...
;         const int m0 = gw * 16, b = m0 / T;
;         f32x4 gm[4], sh[4];
; #pragma unroll
;         for (int j = 0; j < 4; ++j) { const int col = P1COL(j); const f32x4 g = *(const f32x4*)(norm_g + col), scl = *(const f32x4*)(ADA + b * 3072 + 1024 + col);
;             gm[j] = g * (scl + 1.0f); sh[j] = *(const f32x4*)(ADA + b * 3072 + col); }
;         const float bfv = b_f[lane & 7]; f32x4 lsq[4];
; #pragma unroll
;         for (int k = 0; k < 4; ++k) lsq[k] = (f32x4){0.f, 0.f, 0.f, 0.f};
;         for (int r = 0; r < 16; ++r) { const int m = m0 + r;
;             const GAS float* xr = (const GAS float*)(x + (size_t)m * D);
;             f32x4 v[4]; float s2 = 0.f;
; #pragma unroll
;             for (int j = 0; j < 4; ++j) { v[j] = *(const GAS f32x4*)(xr + P1COL(j)); s2 += (v[j][0] * v[j][0] + v[j][1] * v[j][1]) + (v[j][2] * v[j][2] + v[j][3] * v[j][3]); }
;             const float rstd = 1.0f / sqrtf(wave_sum(s2) * (1.0f / D) + EPS);
; #pragma unroll
;             for (int j = 0; j < 4; ++j) v[j] = v[j] * rstd * gm[j] + sh[j];
.LBB0_130:
	s_or_b64 exec, exec, s[8:9]
	s_ashr_i32 s43, s15, 6
	s_lshl_b32 s8, s14, 3
	s_add_i32 s33, s8, s43
	s_ashr_i32 s8, s33, 31
	s_lshr_b32 s8, s8, 24
	s_add_i32 s8, s33, s8
	s_ashr_i32 s44, s8, 8
	s_mul_i32 s8, s44, 0xc00
	s_ashr_i32 s9, s8, 31
	s_lshl_b64 s[8:9], s[8:9], 2
	s_add_u32 s8, s26, s8
	s_addc_u32 s9, s27, s9
	s_add_u32 s10, s8, 0x1000
	s_addc_u32 s11, s9, 0
	s_lshl_b32 s28, s33, 4
	s_ashr_i32 s29, s28, 31
	s_lshl_b64 s[12:13], s[28:29], 12
	v_and_b32_e32 v1, 63, v34
	s_waitcnt lgkmcnt(0)
	s_add_u32 s30, s6, s12
	v_lshlrev_b32_e32 v54, 5, v1
	s_addc_u32 s31, s7, s13
	s_barrier
	global_load_dwordx4 v[26:29], v54, s[30:31]
	global_load_dwordx4 v[18:21], v54, s[30:31] offset:16
	global_load_dwordx4 v[22:25], v54, s[30:31] offset:2064
	global_load_dwordx4 v[30:33], v54, s[30:31] offset:2048
	global_load_dwordx4 v[38:41], v54, s[10:11] offset:16
	global_load_dwordx4 v[42:45], v54, s[10:11]
	v_mbcnt_lo_u32_b32 v3, -1, 0
	v_and_b32_e32 v2, 7, v34
	v_mbcnt_hi_u32_b32 v35, -1, v3
	v_or_b32_e32 v3, 0x800, v54
	v_lshlrev_b32_e32 v2, 2, v2
	global_load_dwordx4 v[46:49], v3, s[10:11] offset:16
	global_load_dwordx4 v[50:53], v3, s[10:11]
	global_load_dwordx4 v[58:61], v54, s[20:21] offset:16
	global_load_dwordx4 v[62:65], v54, s[20:21]
	global_load_dwordx4 v[74:77], v54, s[20:21] offset:2064
	global_load_dwordx4 v[78:81], v54, s[20:21] offset:2048
	global_load_dword v71, v2, s[4:5]
	v_xor_b32_e32 v83, 16, v35
	v_and_b32_e32 v68, 64, v35
	v_mov_b32_e32 v37, 0
	v_lshlrev_b32_e32 v36, 4, v1
	v_xor_b32_e32 v4, 1, v35
	v_add_u32_e32 v87, 64, v68
	s_mov_b64 s[12:13], 0x2000000
	v_xor_b32_e32 v5, 2, v35
	v_lshl_add_u64 v[2:3], s[26:27], 0, v[36:37]
	v_cmp_lt_i32_e32 vcc, v4, v87
	v_lshl_add_u64 v[56:57], v[2:3], 0, s[12:13]
	v_xor_b32_e32 v55, 4, v35
	v_cndmask_b32_e32 v2, v35, v4, vcc
	v_cmp_lt_i32_e32 vcc, v5, v87
	v_lshlrev_b32_e32 v165, 2, v2
	v_xor_b32_e32 v73, 8, v35
	v_cndmask_b32_e32 v88, v35, v5, vcc
	global_load_dwordx4 v[2:5], v54, s[8:9] offset:16
	global_load_dwordx4 v[6:9], v54, s[8:9]
	v_lshlrev_b32_e32 v169, 2, v88
	v_cmp_lt_i32_e32 vcc, v55, v87
	v_xor_b32_e32 v86, 32, v35
	v_mov_b32_e32 v69, 0x358637bd
	v_cndmask_b32_e32 v55, v35, v55, vcc
	v_lshlrev_b32_e32 v168, 2, v55
	v_cmp_lt_i32_e32 vcc, v73, v87
	s_mov_b32 s45, 0xf800000
	v_mov_b32_e32 v70, 0x260
	v_cndmask_b32_e32 v73, v35, v73, vcc
	v_lshlrev_b32_e32 v167, 2, v73
	v_cmp_lt_i32_e32 vcc, v83, v87
	s_lshl_b64 s[34:35], s[28:29], 11
	v_add_u32_e32 v72, 0, v54
	s_or_b32 s36, s28, 1
	s_ashr_i32 s37, s36, 31
	v_cmp_eq_u32_e64 s[10:11], 4, v1
	v_cmp_eq_u32_e64 s[12:13], 5, v1
	v_cmp_eq_u32_e64 s[14:15], 6, v1
	v_cmp_eq_u32_e64 s[16:17], 7, v1
	s_mov_b32 s29, 0xbfb8aa3b
	s_mov_b32 s46, 0x7f800000
	s_mov_b32 s47, 0x33800000
	s_movk_i32 s48, 0x2000
	s_mov_b64 s[38:39], 0x2800
	s_mov_b64 s[40:41], 0x800
	s_waitcnt vmcnt(14)
	v_pk_mul_f32 v[10:11], v[28:29], v[28:29]
	v_pk_mul_f32 v[12:13], v[26:27], v[26:27]
	s_waitcnt vmcnt(13)
	v_pk_mul_f32 v[14:15], v[20:21], v[20:21]
	v_pk_mul_f32 v[16:17], v[18:19], v[18:19]
	v_pk_mov_b32 v[84:85], v[12:13], v[10:11] op_sel:[1,0]
	v_mov_b32_e32 v13, v11
	v_pk_mov_b32 v[10:11], v[16:17], v[14:15] op_sel:[1,0]
	v_mov_b32_e32 v17, v15
	s_waitcnt vmcnt(11)
	v_mul_f32_e32 v66, v31, v31
	v_mul_f32_e32 v82, v33, v33
	v_pk_add_f32 v[12:13], v[84:85], v[12:13]
	v_pk_add_f32 v[10:11], v[10:11], v[16:17]
	v_mul_f32_e32 v89, v22, v22
	v_mul_f32_e32 v90, v23, v23
	v_mul_f32_e32 v91, v24, v24
	v_mul_f32_e32 v92, v25, v25
	v_pk_fma_f32 v[14:15], v[30:31], v[30:31], v[66:67] op_sel_hi:[1,1,0]
	v_pk_fma_f32 v[66:67], v[32:33], v[32:33], v[82:83] op_sel_hi:[1,1,0]
	v_pk_add_f32 v[12:13], v[12:13], v[12:13] op_sel:[0,1] op_sel_hi:[1,0]
	v_pk_add_f32 v[10:11], v[10:11], v[10:11] op_sel:[0,1] op_sel_hi:[1,0]
	v_mov_b32_e32 v15, v91
	v_mov_b32_e32 v67, v92
	v_mov_b32_e32 v13, v89
	v_mov_b32_e32 v11, v90
	v_pk_add_f32 v[14:15], v[14:15], v[66:67]
	v_pk_add_f32 v[10:11], v[12:13], v[10:11]
	v_cndmask_b32_e32 v82, v35, v83, vcc
	v_pk_add_f32 v[10:11], v[10:11], v[14:15]
	v_lshlrev_b32_e32 v166, 2, v82
	v_add_f32_e32 v66, v10, v11
	global_load_dwordx4 v[10:13], v54, s[8:9] offset:2064
	global_load_dwordx4 v[14:17], v54, s[8:9] offset:2048
	s_waitcnt vmcnt(12)
	v_pk_add_f32 v[82:83], v[38:39], 1.0 op_sel_hi:[1,0]
	v_cmp_lt_i32_e32 vcc, v86, v87
	s_waitcnt vmcnt(11)
	v_pk_add_f32 v[44:45], v[44:45], 1.0 op_sel_hi:[1,0]
	s_waitcnt vmcnt(9)
	v_pk_add_f32 v[52:53], v[52:53], 1.0 op_sel_hi:[1,0]
	s_waitcnt lgkmcnt(0)
	s_nop 1
	v_add_f32_dpp v66, v66, v66 quad_perm:[1,0,3,2] row_mask:0xf bank_mask:0xf
	v_pk_add_f32 v[42:43], v[42:43], 1.0 op_sel_hi:[1,0]
	v_pk_add_f32 v[50:51], v[50:51], 1.0 op_sel_hi:[1,0]
	v_pk_add_f32 v[84:85], v[48:49], 1.0 op_sel_hi:[1,0]
	s_waitcnt vmcnt(5)
	v_pk_mul_f32 v[48:49], v[78:79], v[50:51]
	s_waitcnt lgkmcnt(0)
	s_nop 1
	v_add_f32_dpp v55, v66, v66 quad_perm:[2,3,0,1] row_mask:0xf bank_mask:0xf
	v_cndmask_b32_e32 v67, v35, v86, vcc
	v_lshlrev_b32_e32 v164, 2, v67
	v_pk_add_f32 v[86:87], v[46:47], 1.0 op_sel_hi:[1,0]
	v_pk_mul_f32 v[50:51], v[76:77], v[84:85]
	s_waitcnt lgkmcnt(0)
	s_nop 1
	v_add_f32_dpp v55, v55, v55 row_half_mirror row_mask:0xf bank_mask:0xf
	v_pk_add_f32 v[66:67], v[40:41], 1.0 op_sel_hi:[1,0]
	v_pk_mul_f32 v[40:41], v[62:63], v[42:43]
	v_pk_mul_f32 v[42:43], v[60:61], v[66:67]
	v_cmp_eq_u32_e64 s[8:9], 3, v1
	s_waitcnt lgkmcnt(0)
	s_nop 1
	v_add_f32_dpp v38, v55, v55 row_mirror row_mask:0xf bank_mask:0xf
	s_waitcnt lgkmcnt(0)
	v_mov_b32_e32 v39, v38
	v_mov_b32_e32 v46, v38
	s_nop 1
	v_permlane16_swap_b32_e32 v39, v46
	v_add_f32_e32 v46, v39, v46
	v_pk_mul_f32 v[38:39], v[64:65], v[44:45]
	v_pk_mul_f32 v[44:45], v[58:59], v[82:83]
	s_waitcnt lgkmcnt(0)
; #define GAS __attribute__((address_space(1)))
; #define LAS __attribute__((address_space(3)))
; __device__ __forceinline__ unsigned pk2(float lo, float hi) { return pg8::cvt_pk_bf16(lo, hi); }
; template <int LO, int HI> __global__ void __launch_bounds__(NWAVES * 64, 2) fox_fwd(Args args) {
;     ...
;             for (int j = 0; j < 4; ++j) { v[j] = *(const GAS f32x4*)(xr + P1COL(j)); s2 += (v[j][0] * v[j][0] + v[j][1] * v[j][1]) + (v[j][2] * v[j][2] + v[j][3] * v[j][3]); }
;             const float rstd = 1.0f / sqrtf(wave_sum(s2) * (1.0f / D) + EPS);
; #pragma unroll
;             for (int j = 0; j < 4; ++j) v[j] = v[j] * rstd * gm[j] + sh[j];
; #pragma unroll
;             for (int j = 0; j < 2; ++j) { v4u o; o.x = pk2(v[2 * j][0], v[2 * j][1]); o.y = pk2(v[2 * j][2], v[2 * j][3]); o.z = pk2(v[2 * j + 1][0], v[2 * j + 1][1]); o.w = pk2(v[2 * j + 1][2], v[2 * j + 1][3]);
;                 *(GAS v4u*)(HB + (size_t)m * D + 8 * lane + 512 * j) = o; }
;             float fl[8];
; #pragma unroll
;             for (int q = 0; q < 8; ++q) { float a = 0.f;
; #pragma unroll
;                 for (int j = 0; j < 4; ++j) { const f32x4 w = *(const LAS f32x4*)(wf + q * 1024 + P1COL(j)); a += (v[j][0] * w[0] + v[j][1] * w[1]) + (v[j][2] * w[2] + v[j][3] * w[3]); }
;                 fl[q] = wave_sum(a); }
	v_mov_b32_e32 v47, v46
	s_nop 1
	v_permlane32_swap_b32_e32 v47, v46
	v_add_f32_e32 v46, v47, v46
	v_fmamk_f32 v46, v46, 0x3a800000, v69
	v_mul_f32_e32 v47, 0x4f800000, v46
	v_cmp_gt_f32_e32 vcc, s45, v46
	s_nop 1
	v_cndmask_b32_e32 v55, v46, v47, vcc
	v_sqrt_f32_e32 v58, v55
	v_pk_mul_f32 v[46:47], v[80:81], v[52:53]
	v_add_u32_e32 v52, -1, v58
	v_add_u32_e32 v53, 1, v58
	v_fma_f32 v59, -v52, v58, v55
	v_fma_f32 v60, -v53, v58, v55
	v_cmp_ge_f32_e64 s[4:5], 0, v59
	s_nop 1
	v_cndmask_b32_e64 v52, v58, v52, s[4:5]
	v_cmp_lt_f32_e64 s[4:5], 0, v60
	s_nop 1
	v_cndmask_b32_e64 v52, v52, v53, s[4:5]
	v_mul_f32_e32 v53, 0x37800000, v52
	v_cndmask_b32_e32 v52, v52, v53, vcc
	v_cmp_class_f32_e32 vcc, v55, v70
	s_nop 1
	v_cndmask_b32_e32 v55, v52, v55, vcc
	v_div_scale_f32 v58, s[4:5], v55, v55, 1.0
	v_rcp_f32_e32 v59, v58
	v_div_scale_f32 v60, vcc, 1.0, v55, 1.0
	v_pk_mul_f32 v[52:53], v[74:75], v[86:87]
	v_fma_f32 v61, -v58, v59, 1.0
	v_fmac_f32_e32 v59, v61, v59
	v_mul_f32_e32 v61, v60, v59
	v_fma_f32 v62, -v58, v61, v60
	v_fmac_f32_e32 v61, v62, v59
	v_fma_f32 v58, -v58, v61, v60
	v_div_fmas_f32 v58, v58, v59, v61
	v_div_fixup_f32 v64, v58, v55, 1.0
	v_pk_mul_f32 v[18:19], v[64:65], v[18:19] op_sel_hi:[0,1]
	v_pk_mul_f32 v[20:21], v[64:65], v[20:21] op_sel_hi:[0,1]
	s_waitcnt vmcnt(3)
	v_pk_fma_f32 v[60:61], v[42:43], v[20:21], v[4:5]
	v_pk_fma_f32 v[62:63], v[44:45], v[18:19], v[2:3]
	v_pk_mul_f32 v[18:19], v[64:65], v[30:31] op_sel_hi:[0,1]
	v_pk_mul_f32 v[20:21], v[64:65], v[32:33] op_sel_hi:[0,1]
	v_pk_mul_f32 v[58:59], v[64:65], v[26:27] op_sel_hi:[0,1]
	v_pk_mul_f32 v[26:27], v[64:65], v[28:29] op_sel_hi:[0,1]
	s_waitcnt vmcnt(0)
	v_pk_fma_f32 v[28:29], v[46:47], v[20:21], v[16:17]
	v_pk_fma_f32 v[30:31], v[48:49], v[18:19], v[14:15]
	v_pk_mul_f32 v[18:19], v[64:65], v[22:23] op_sel_hi:[0,1]
	v_pk_mul_f32 v[20:21], v[64:65], v[24:25] op_sel_hi:[0,1]
	v_pk_fma_f32 v[26:27], v[38:39], v[26:27], v[8:9]
	v_pk_fma_f32 v[58:59], v[40:41], v[58:59], v[6:7]
	v_pk_fma_f32 v[22:23], v[50:51], v[20:21], v[12:13]
	v_pk_fma_f32 v[24:25], v[52:53], v[18:19], v[10:11]
	v_lshl_add_u64 v[32:33], v[56:57], 0, s[34:35]
	v_cvt_pk_bf16_f32 v18, v58, v59
	v_cvt_pk_bf16_f32 v19, v26, v27
	v_cvt_pk_bf16_f32 v20, v62, v63
	v_cvt_pk_bf16_f32 v21, v60, v61
	global_store_dwordx4 v[32:33], v[18:21], off
	s_lshl_b64 s[4:5], s[36:37], 12
	s_add_u32 s4, s6, s4
	v_cvt_pk_bf16_f32 v18, v30, v31
	v_cvt_pk_bf16_f32 v19, v28, v29
	v_cvt_pk_bf16_f32 v20, v24, v25
	v_cvt_pk_bf16_f32 v21, v22, v23
	ds_read_b128 v[64:67], v72
	ds_read_b128 v[74:77], v72 offset:16
	global_store_dwordx4 v[32:33], v[18:21], off offset:1024
	ds_read_b128 v[18:21], v72 offset:12288
	s_addc_u32 s5, s7, s5
	s_waitcnt lgkmcnt(2)
	v_mul_f32_e32 v55, v59, v65
	v_fmac_f32_e32 v55, v58, v64
	v_mul_f32_e32 v64, v27, v67
	v_fmac_f32_e32 v64, v26, v66
	v_add_f32_e32 v55, v55, v64
	ds_read_b128 v[64:67], v72 offset:2048
	s_waitcnt lgkmcnt(2)
	v_mul_f32_e32 v73, v63, v75
	v_fmac_f32_e32 v73, v62, v74
	v_mul_f32_e32 v74, v61, v77
	v_fmac_f32_e32 v74, v60, v76
	v_add_f32_e32 v73, v73, v74
	ds_read_b128 v[74:77], v72 offset:2064
	s_waitcnt lgkmcnt(1)
	v_mul_f32_e32 v65, v31, v65
	v_fmac_f32_e32 v65, v30, v64
	v_mul_f32_e32 v64, v29, v67
	v_add_f32_e32 v55, 0, v55
	v_fmac_f32_e32 v64, v28, v66
	v_add_f32_e32 v55, v55, v73
	v_add_f32_e32 v64, v65, v64
	v_add_f32_e32 v55, v55, v64
	s_waitcnt lgkmcnt(0)
	v_mul_f32_e32 v64, v25, v75
	v_mul_f32_e32 v65, v23, v77
	v_fmac_f32_e32 v64, v24, v74
	v_fmac_f32_e32 v65, v22, v76
	v_add_f32_e32 v64, v64, v65
	v_add_f32_e32 v55, v55, v64
	ds_read_b128 v[74:77], v72 offset:4112
	v_cmp_eq_u32_e64 s[6:7], 2, v1
	s_waitcnt lgkmcnt(1)
	s_nop 1
	v_add_f32_dpp v55, v55, v55 quad_perm:[1,0,3,2] row_mask:0xf bank_mask:0xf
	s_waitcnt lgkmcnt(0)
	v_mul_f32_e32 v75, v63, v75
	v_fmac_f32_e32 v75, v62, v74
	v_mul_f32_e32 v74, v61, v77
	v_fmac_f32_e32 v74, v60, v76
	s_waitcnt lgkmcnt(0)
	s_nop 1
	v_add_f32_dpp v55, v55, v55 quad_perm:[2,3,0,1] row_mask:0xf bank_mask:0xf
	ds_read_b128 v[64:67], v72 offset:4096
	v_add_f32_e32 v74, v75, v74
	s_waitcnt lgkmcnt(0)
	v_mul_f32_e32 v65, v59, v65
	v_fmac_f32_e32 v65, v58, v64
	v_mul_f32_e32 v64, v27, v67
	v_fmac_f32_e32 v64, v26, v66
	v_add_f32_e32 v64, v65, v64
	v_add_f32_e32 v78, 0, v64
	ds_read_b128 v[64:67], v72 offset:6144
	v_add_f32_e32 v78, v78, v74
	ds_read_b128 v[74:77], v72 offset:6160
	s_waitcnt lgkmcnt(2)
	s_nop 1
	v_add_f32_dpp v55, v55, v55 row_half_mirror row_mask:0xf bank_mask:0xf
	s_waitcnt lgkmcnt(1)
	v_mul_f32_e32 v65, v31, v65
	v_fmac_f32_e32 v65, v30, v64
	v_mul_f32_e32 v64, v29, v67
	v_fmac_f32_e32 v64, v28, v66
	v_add_f32_e32 v64, v65, v64
	s_waitcnt lgkmcnt(0)
	v_mul_f32_e32 v65, v25, v75
	v_mul_f32_e32 v66, v23, v77
	v_fmac_f32_e32 v65, v24, v74
	v_fmac_f32_e32 v66, v22, v76
	v_add_f32_e32 v64, v78, v64
	v_add_f32_e32 v65, v65, v66
	v_add_f32_e32 v64, v64, v65
	s_waitcnt lgkmcnt(0)
	s_nop 1
	v_add_f32_dpp v55, v55, v55 row_mirror row_mask:0xf bank_mask:0xf
	v_lshlrev_b32_e32 v73, 3, v1
	s_waitcnt lgkmcnt(0)
	s_nop 1
	v_add_f32_dpp v75, v64, v64 quad_perm:[1,0,3,2] row_mask:0xf bank_mask:0xf
	ds_read_b128 v[64:67], v72 offset:8192
	s_waitcnt lgkmcnt(1)
	v_mov_b32_e32 v74, v55
	s_nop 1
	v_permlane16_swap_b32_e32 v74, v55
	v_add_f32_e32 v55, v74, v55
	s_waitcnt lgkmcnt(1)
	s_nop 1
	v_add_f32_dpp v78, v75, v75 quad_perm:[2,3,0,1] row_mask:0xf bank_mask:0xf
	ds_read_b128 v[74:77], v72 offset:8208
	s_waitcnt lgkmcnt(1)
	v_mul_f32_e32 v65, v59, v65
	v_fmac_f32_e32 v65, v58, v64
	v_mul_f32_e32 v64, v27, v67
	v_fmac_f32_e32 v64, v26, v66
	v_add_f32_e32 v64, v65, v64
	s_waitcnt lgkmcnt(0)
; #define LAS __attribute__((address_space(3)))
; template <int LO, int HI> __global__ void __launch_bounds__(NWAVES * 64, 2) fox_fwd(Args args) {
;     ...
;             for (int q = 0; q < 8; ++q) { float a = 0.f;
; #pragma unroll
;                 for (int j = 0; j < 4; ++j) { const f32x4 w = *(const LAS f32x4*)(wf + q * 1024 + P1COL(j)); a += (v[j][0] * w[0] + v[j][1] * w[1]) + (v[j][2] * w[2] + v[j][3] * w[3]); }
;                 fl[q] = wave_sum(a); }
	v_mul_f32_e32 v75, v63, v75
	v_add_f32_e32 v80, 0, v64
	v_fmac_f32_e32 v75, v62, v74
	v_mul_f32_e32 v74, v61, v77
	ds_read_b128 v[64:67], v72 offset:10240
	v_fmac_f32_e32 v74, v60, v76
	v_add_f32_e32 v74, v75, v74
	v_add_f32_e32 v80, v80, v74
	ds_read_b128 v[74:77], v72 offset:10256
	s_waitcnt lgkmcnt(1)
	v_mul_f32_e32 v65, v31, v65
	v_fmac_f32_e32 v65, v30, v64
	v_mul_f32_e32 v64, v29, v67
	v_fmac_f32_e32 v64, v28, v66
	v_add_f32_e32 v64, v65, v64
	s_waitcnt lgkmcnt(0)
	v_mul_f32_e32 v65, v25, v75
	v_mul_f32_e32 v66, v23, v77
	v_fmac_f32_e32 v65, v24, v74
	v_fmac_f32_e32 v66, v22, v76
	v_add_f32_e32 v64, v80, v64
	v_add_f32_e32 v65, v65, v66
	v_add_f32_e32 v64, v64, v65
	s_waitcnt lgkmcnt(0)
	s_nop 1
	v_add_f32_dpp v67, v78, v78 row_half_mirror row_mask:0xf bank_mask:0xf
	s_waitcnt lgkmcnt(0)
	s_nop 1
	v_add_f32_dpp v32, v64, v64 quad_perm:[1,0,3,2] row_mask:0xf bank_mask:0xf
	s_waitcnt lgkmcnt(0)
	v_mov_b32_e32 v66, v55
	s_nop 1
	v_permlane32_swap_b32_e32 v66, v55
	v_add_f32_e32 v55, v66, v55
	s_waitcnt lgkmcnt(0)
	s_nop 1
	v_add_f32_dpp v74, v67, v67 row_mirror row_mask:0xf bank_mask:0xf
	ds_read_b128 v[64:67], v72 offset:12304
	v_mul_f32_e32 v19, v59, v19
	v_fmac_f32_e32 v19, v58, v18
	v_mul_f32_e32 v18, v27, v21
	v_fmac_f32_e32 v18, v26, v20
	v_add_f32_e32 v18, v19, v18
	s_waitcnt lgkmcnt(0)
	v_mul_f32_e32 v65, v63, v65
	v_add_f32_e32 v76, 0, v18
	v_fmac_f32_e32 v65, v62, v64
	v_mul_f32_e32 v64, v61, v67
	ds_read_b128 v[18:21], v72 offset:14336
	v_fmac_f32_e32 v64, v60, v66
	v_add_f32_e32 v64, v65, v64
	v_add_f32_e32 v76, v76, v64
	ds_read_b128 v[64:67], v72 offset:14352
	s_waitcnt lgkmcnt(1)
	v_mul_f32_e32 v19, v31, v19
	v_fmac_f32_e32 v19, v30, v18
	v_mul_f32_e32 v18, v29, v21
	v_fmac_f32_e32 v18, v28, v20
	v_add_f32_e32 v18, v19, v18
	s_waitcnt lgkmcnt(0)
	v_mul_f32_e32 v19, v25, v65
	v_mul_f32_e32 v20, v23, v67
	v_fmac_f32_e32 v19, v24, v64
	v_fmac_f32_e32 v20, v22, v66
	v_add_f32_e32 v18, v76, v18
	v_add_f32_e32 v19, v19, v20
	v_add_f32_e32 v64, v18, v19
	ds_read_b128 v[18:21], v72 offset:16384
	s_waitcnt lgkmcnt(1)
	v_mov_b32_e32 v75, v74
	s_nop 1
	v_permlane16_swap_b32_e32 v75, v74
	v_add_f32_e32 v74, v75, v74
	s_waitcnt lgkmcnt(1)
	s_nop 1
	v_add_f32_dpp v75, v64, v64 quad_perm:[1,0,3,2] row_mask:0xf bank_mask:0xf
	ds_read_b128 v[64:67], v72 offset:16400
	s_waitcnt lgkmcnt(1)
	v_mul_f32_e32 v19, v59, v19
	v_fmac_f32_e32 v19, v58, v18
	v_mul_f32_e32 v18, v27, v21
	v_fmac_f32_e32 v18, v26, v20
	v_add_f32_e32 v18, v19, v18
	s_waitcnt lgkmcnt(0)
	v_mul_f32_e32 v65, v63, v65
	v_add_f32_e32 v77, 0, v18
	v_fmac_f32_e32 v65, v62, v64
	v_mul_f32_e32 v64, v61, v67
	ds_read_b128 v[18:21], v72 offset:18432
	v_fmac_f32_e32 v64, v60, v66
	v_add_f32_e32 v64, v65, v64
	s_nop 1
	v_add_f32_dpp v32, v32, v32 quad_perm:[2,3,0,1] row_mask:0xf bank_mask:0xf
	v_add_f32_e32 v77, v77, v64
	ds_read_b128 v[64:67], v72 offset:18448
	s_waitcnt lgkmcnt(1)
	v_mul_f32_e32 v19, v31, v19
	v_fmac_f32_e32 v19, v30, v18
	v_mul_f32_e32 v18, v29, v21
	v_fmac_f32_e32 v18, v28, v20
	v_add_f32_e32 v18, v19, v18
	s_waitcnt lgkmcnt(0)
	v_mul_f32_e32 v19, v25, v65
	v_mul_f32_e32 v20, v23, v67
	s_waitcnt lgkmcnt(0)
	s_nop 1
	v_add_f32_dpp v32, v32, v32 row_half_mirror row_mask:0xf bank_mask:0xf
	v_fmac_f32_e32 v19, v24, v64
	v_fmac_f32_e32 v20, v22, v66
	v_add_f32_e32 v18, v77, v18
	v_add_f32_e32 v19, v19, v20
	v_add_f32_e32 v18, v18, v19
	s_waitcnt lgkmcnt(0)
	s_nop 1
	v_add_f32_dpp v21, v75, v75 quad_perm:[2,3,0,1] row_mask:0xf bank_mask:0xf
	s_waitcnt lgkmcnt(0)
	s_nop 1
	v_add_f32_dpp v20, v32, v32 row_mirror row_mask:0xf bank_mask:0xf
	s_waitcnt lgkmcnt(0)
	s_nop 1
	v_add_f32_dpp v18, v18, v18 quad_perm:[1,0,3,2] row_mask:0xf bank_mask:0xf
	s_waitcnt lgkmcnt(0)
	s_nop 1
	v_add_f32_dpp v21, v21, v21 row_half_mirror row_mask:0xf bank_mask:0xf
	s_waitcnt lgkmcnt(0)
	v_mov_b32_e32 v33, v20
	s_nop 1
	v_permlane16_swap_b32_e32 v33, v20
	v_add_f32_e32 v20, v33, v20
	s_waitcnt lgkmcnt(0)
	s_nop 1
	v_add_f32_dpp v18, v18, v18 quad_perm:[2,3,0,1] row_mask:0xf bank_mask:0xf
	s_waitcnt lgkmcnt(0)
	s_nop 1
	v_add_f32_dpp v21, v21, v21 row_mirror row_mask:0xf bank_mask:0xf
	v_mov_b32_e32 v64, v74
	s_nop 1
	v_permlane32_swap_b32_e32 v64, v74
	v_add_f32_e32 v74, v64, v74
	s_waitcnt lgkmcnt(0)
	s_nop 1
	v_add_f32_dpp v64, v18, v18 row_half_mirror row_mask:0xf bank_mask:0xf
	s_waitcnt lgkmcnt(0)
	v_mov_b32_e32 v33, v20
	v_mov_b32_e32 v75, v20
	s_nop 1
	v_permlane32_swap_b32_e32 v33, v75
	v_add_f32_e32 v75, v33, v75
	s_waitcnt lgkmcnt(0)
	v_mov_b32_e32 v32, v21
	s_nop 1
	v_permlane16_swap_b32_e32 v32, v21
	v_add_f32_e32 v32, v32, v21
	ds_read_b128 v[18:21], v72 offset:20480
	s_waitcnt lgkmcnt(1)
	s_nop 1
	v_add_f32_dpp v76, v64, v64 row_mirror row_mask:0xf bank_mask:0xf
	ds_read_b128 v[64:67], v72 offset:20496
	s_waitcnt lgkmcnt(1)
	v_mul_f32_e32 v19, v59, v19
	v_fmac_f32_e32 v19, v58, v18
	v_mul_f32_e32 v18, v27, v21
	v_fmac_f32_e32 v18, v26, v20
	v_add_f32_e32 v18, v19, v18
	s_waitcnt lgkmcnt(0)
	v_mul_f32_e32 v65, v63, v65
	v_add_f32_e32 v78, 0, v18
	v_fmac_f32_e32 v65, v62, v64
	v_mul_f32_e32 v64, v61, v67
	ds_read_b128 v[18:21], v72 offset:22528
	v_fmac_f32_e32 v64, v60, v66
	v_add_f32_e32 v64, v65, v64
	v_add_f32_e32 v78, v78, v64
	ds_read_b128 v[64:67], v72 offset:22544
	s_waitcnt lgkmcnt(1)
	v_mul_f32_e32 v19, v31, v19
	v_fmac_f32_e32 v19, v30, v18
	v_mul_f32_e32 v18, v29, v21
	v_fmac_f32_e32 v18, v28, v20
	v_add_f32_e32 v18, v19, v18
	s_waitcnt lgkmcnt(0)
; #define GAS __attribute__((address_space(1)))
; #define LAS __attribute__((address_space(3)))
; __device__ __forceinline__ unsigned pk2(float lo, float hi) { return pg8::cvt_pk_bf16(lo, hi); }
; template <int LO, int HI> __global__ void __launch_bounds__(NWAVES * 64, 2) fox_fwd(Args args) {
;     ...
;         for (int r = 0; r < 16; ++r) { const int m = m0 + r;
;             const GAS float* xr = (const GAS float*)(x + (size_t)m * D);
;             f32x4 v[4]; float s2 = 0.f;
; #pragma unroll
;             for (int j = 0; j < 4; ++j) { v[j] = *(const GAS f32x4*)(xr + P1COL(j)); s2 += (v[j][0] * v[j][0] + v[j][1] * v[j][1]) + (v[j][2] * v[j][2] + v[j][3] * v[j][3]); }
;             const float rstd = 1.0f / sqrtf(wave_sum(s2) * (1.0f / D) + EPS);
; #pragma unroll
;             for (int j = 0; j < 4; ++j) v[j] = v[j] * rstd * gm[j] + sh[j];
; #pragma unroll
;             for (int j = 0; j < 2; ++j) { v4u o; o.x = pk2(v[2 * j][0], v[2 * j][1]); o.y = pk2(v[2 * j][2], v[2 * j][3]); o.z = pk2(v[2 * j + 1][0], v[2 * j + 1][1]); o.w = pk2(v[2 * j + 1][2], v[2 * j + 1][3]);
;                 *(GAS v4u*)(HB + (size_t)m * D + 8 * lane + 512 * j) = o; }
;             float fl[8];
; #pragma unroll
;             for (int q = 0; q < 8; ++q) { float a = 0.f;
; #pragma unroll
;                 for (int j = 0; j < 4; ++j) { const f32x4 w = *(const LAS f32x4*)(wf + q * 1024 + P1COL(j)); a += (v[j][0] * w[0] + v[j][1] * w[1]) + (v[j][2] * w[2] + v[j][3] * w[3]); }
;                 fl[q] = wave_sum(a); }
	v_mul_f32_e32 v19, v25, v65
	v_mul_f32_e32 v20, v23, v67
	v_fmac_f32_e32 v19, v24, v64
	v_fmac_f32_e32 v20, v22, v66
	v_add_f32_e32 v18, v78, v18
	v_add_f32_e32 v19, v19, v20
	v_add_f32_e32 v64, v18, v19
	ds_read_b128 v[18:21], v72 offset:24576
	v_mov_b32_e32 v33, v32
	v_mov_b32_e32 v92, v32
	s_nop 1
	v_permlane32_swap_b32_e32 v33, v92
	v_add_f32_e32 v92, v33, v92
	v_mov_b32_e32 v77, v76
	v_mov_b32_e32 v93, v76
	s_nop 1
	v_permlane16_swap_b32_e32 v77, v93
	v_add_f32_e32 v93, v77, v93
	s_waitcnt lgkmcnt(1)
	s_nop 1
	v_add_f32_dpp v95, v64, v64 quad_perm:[1,0,3,2] row_mask:0xf bank_mask:0xf
	ds_read_b128 v[64:67], v72 offset:24592
	s_waitcnt lgkmcnt(1)
	v_pk_mul_f32 v[18:19], v[58:59], v[18:19]
	v_pk_mul_f32 v[20:21], v[26:27], v[20:21]
	v_pk_mov_b32 v[32:33], v[18:19], v[20:21] op_sel:[1,0]
	v_mov_b32_e32 v19, v21
	v_pk_add_f32 v[18:19], v[32:33], v[18:19]
	s_waitcnt lgkmcnt(0)
	v_pk_mul_f32 v[64:65], v[62:63], v[64:65]
	v_add_f32_e32 v18, v18, v19
	v_add_f32_e32 v32, 0, v18
	ds_read_b128 v[18:21], v72 offset:26624
	ds_read_b128 v[76:79], v72 offset:26640
	global_load_dwordx4 v[80:83], v54, s[4:5] offset:16
	global_load_dwordx4 v[84:87], v54, s[4:5]
	v_pk_mul_f32 v[66:67], v[60:61], v[66:67]
	s_waitcnt lgkmcnt(0)
	v_mul_f32_e32 v33, v24, v76
	v_pk_mov_b32 v[88:89], v[64:65], v[66:67] op_sel:[1,0]
	v_mov_b32_e32 v65, v67
	v_pk_add_f32 v[64:65], v[88:89], v[64:65]
	v_mul_f32_e32 v66, v25, v77
	v_mul_f32_e32 v67, v22, v78
	v_mul_f32_e32 v97, v23, v79
	global_load_dwordx4 v[76:79], v54, s[4:5] offset:2048
	global_load_dwordx4 v[88:91], v54, s[4:5] offset:2064
	v_pk_add_f32 v[64:65], v[64:65], v[64:65] op_sel:[0,1] op_sel_hi:[1,0]
	v_cmp_eq_u32_e64 s[4:5], 1, v1
	v_mov_b32_e32 v65, v66
	v_pk_add_f32 v[32:33], v[32:33], v[64:65]
	v_mul_f32_e32 v64, v31, v19
	v_pk_fma_f32 v[18:19], v[30:31], v[18:19], v[64:65] op_sel_hi:[1,1,0]
	v_mul_f32_e32 v64, v29, v21
	v_pk_fma_f32 v[20:21], v[28:29], v[20:21], v[64:65] op_sel_hi:[1,1,0]
	v_mov_b32_e32 v19, v67
	v_mov_b32_e32 v21, v97
	v_pk_add_f32 v[64:65], v[18:19], v[20:21]
	ds_read_b128 v[18:21], v72 offset:28672
	v_pk_add_f32 v[32:33], v[32:33], v[64:65]
	ds_read_b128 v[64:67], v72 offset:28688
	v_add_f32_e32 v97, v32, v33
	s_waitcnt lgkmcnt(1)
	v_pk_mul_f32 v[18:19], v[58:59], v[18:19]
	v_pk_mul_f32 v[20:21], v[26:27], v[20:21]
	s_waitcnt lgkmcnt(0)
	v_pk_mul_f32 v[32:33], v[62:63], v[64:65]
	v_pk_mov_b32 v[26:27], v[18:19], v[20:21] op_sel:[1,0]
	v_mov_b32_e32 v19, v21
	v_pk_add_f32 v[18:19], v[26:27], v[18:19]
	v_pk_mul_f32 v[58:59], v[60:61], v[66:67]
	v_add_f32_e32 v18, v18, v19
	v_add_f32_e32 v26, 0, v18
	ds_read_b128 v[18:21], v72 offset:30720
	ds_read_b128 v[62:65], v72 offset:30736
	v_pk_mov_b32 v[60:61], v[32:33], v[58:59] op_sel:[1,0]
	v_mov_b32_e32 v33, v59
	v_pk_add_f32 v[32:33], v[60:61], v[32:33]
	s_waitcnt lgkmcnt(0)
	v_mul_f32_e32 v27, v24, v62
	v_mul_f32_e32 v24, v25, v63
	v_mul_f32_e32 v25, v22, v64
	v_mul_f32_e32 v58, v23, v65
	v_pk_add_f32 v[22:23], v[32:33], v[32:33] op_sel:[0,1] op_sel_hi:[1,0]
	s_nop 0
	v_mov_b32_e32 v23, v24
	v_mul_f32_e32 v24, v31, v19
	v_pk_fma_f32 v[18:19], v[30:31], v[18:19], v[24:25] op_sel_hi:[1,1,0]
	v_mul_f32_e32 v24, v29, v21
	v_pk_fma_f32 v[20:21], v[28:29], v[20:21], v[24:25] op_sel_hi:[1,1,0]
	v_mov_b32_e32 v19, v25
	v_mov_b32_e32 v21, v58
	v_pk_add_f32 v[22:23], v[26:27], v[22:23]
	v_pk_add_f32 v[18:19], v[18:19], v[20:21]
	s_nop 1
	v_add_f32_dpp v20, v95, v95 quad_perm:[2,3,0,1] row_mask:0xf bank_mask:0xf
	v_pk_add_f32 v[18:19], v[22:23], v[18:19]
	v_add_f32_e32 v18, v18, v19
	s_nop 1
	v_add_f32_dpp v22, v97, v97 quad_perm:[1,0,3,2] row_mask:0xf bank_mask:0xf
	s_waitcnt lgkmcnt(0)
	s_nop 1
	v_add_f32_dpp v20, v20, v20 row_half_mirror row_mask:0xf bank_mask:0xf
	s_waitcnt lgkmcnt(0)
	s_nop 1
	v_add_f32_dpp v18, v18, v18 quad_perm:[1,0,3,2] row_mask:0xf bank_mask:0xf
	s_waitcnt lgkmcnt(0)
	s_nop 1
	v_add_f32_dpp v22, v22, v22 quad_perm:[2,3,0,1] row_mask:0xf bank_mask:0xf
	s_waitcnt lgkmcnt(0)
	s_nop 1
	v_add_f32_dpp v20, v20, v20 row_mirror row_mask:0xf bank_mask:0xf
	s_waitcnt lgkmcnt(0)
	s_nop 1
	v_add_f32_dpp v18, v18, v18 quad_perm:[2,3,0,1] row_mask:0xf bank_mask:0xf
	s_waitcnt lgkmcnt(0)
	s_nop 1
	v_add_f32_dpp v22, v22, v22 row_half_mirror row_mask:0xf bank_mask:0xf
	s_waitcnt lgkmcnt(0)
	v_mov_b32_e32 v21, v20
	v_mov_b32_e32 v26, v20
	s_nop 1
	v_permlane16_swap_b32_e32 v21, v26
	v_add_f32_e32 v26, v21, v26
	s_waitcnt lgkmcnt(0)
	s_nop 1
	v_add_f32_dpp v18, v18, v18 row_half_mirror row_mask:0xf bank_mask:0xf
	s_waitcnt vmcnt(2)
	v_pk_mul_f32 v[20:21], v[84:85], v[84:85]
	s_waitcnt lgkmcnt(0)
	s_nop 1
	v_add_f32_dpp v28, v22, v22 row_mirror row_mask:0xf bank_mask:0xf
	s_waitcnt lgkmcnt(0)
	s_nop 1
	v_add_f32_dpp v30, v18, v18 row_mirror row_mask:0xf bank_mask:0xf
	v_pk_mul_f32 v[18:19], v[86:87], v[86:87]
	v_pk_mov_b32 v[22:23], v[20:21], v[18:19] op_sel:[1,0]
	v_mov_b32_e32 v21, v19
	v_pk_add_f32 v[18:19], v[22:23], v[20:21]
	v_pk_mul_f32 v[20:21], v[82:83], v[82:83]
	v_pk_mul_f32 v[22:23], v[80:81], v[80:81]
	v_pk_add_f32 v[18:19], v[18:19], v[18:19] op_sel:[0,1] op_sel_hi:[1,0]
	v_pk_mov_b32 v[24:25], v[22:23], v[20:21] op_sel:[1,0]
	v_mov_b32_e32 v23, v21
	v_pk_add_f32 v[20:21], v[24:25], v[22:23]
	s_waitcnt vmcnt(0)
	v_mul_f32_e32 v22, v88, v88
	v_mul_f32_e32 v23, v89, v89
	v_pk_add_f32 v[20:21], v[20:21], v[20:21] op_sel:[0,1] op_sel_hi:[1,0]
	v_mov_b32_e32 v19, v22
	v_mov_b32_e32 v21, v23
	v_pk_add_f32 v[18:19], v[18:19], v[20:21]
	v_mul_f32_e32 v20, v77, v77
	v_mul_f32_e32 v22, v79, v79
	v_mul_f32_e32 v24, v90, v90
	v_mul_f32_e32 v25, v91, v91
	v_pk_fma_f32 v[20:21], v[76:77], v[76:77], v[20:21] op_sel_hi:[1,1,0]
	v_pk_fma_f32 v[22:23], v[78:79], v[78:79], v[22:23] op_sel_hi:[1,1,0]
	v_mov_b32_e32 v21, v24
	v_mov_b32_e32 v23, v25
	v_pk_add_f32 v[20:21], v[20:21], v[22:23]
	s_waitcnt lgkmcnt(0)
; #define GAS __attribute__((address_space(1)))
; #define LAS __attribute__((address_space(3)))
; __device__ __forceinline__ unsigned pk2(float lo, float hi) { return pg8::cvt_pk_bf16(lo, hi); }
; template <int LO, int HI> __global__ void __launch_bounds__(NWAVES * 64, 2) fox_fwd(Args args) {
;     ...
;         for (int r = 0; r < 16; ++r) { const int m = m0 + r;
;             const GAS float* xr = (const GAS float*)(x + (size_t)m * D);
;             f32x4 v[4]; float s2 = 0.f;
; #pragma unroll
;             for (int j = 0; j < 4; ++j) { v[j] = *(const GAS f32x4*)(xr + P1COL(j)); s2 += (v[j][0] * v[j][0] + v[j][1] * v[j][1]) + (v[j][2] * v[j][2] + v[j][3] * v[j][3]); }
;             const float rstd = 1.0f / sqrtf(wave_sum(s2) * (1.0f / D) + EPS);
; #pragma unroll
;             for (int j = 0; j < 4; ++j) v[j] = v[j] * rstd * gm[j] + sh[j];
; #pragma unroll
;             for (int j = 0; j < 2; ++j) { v4u o; o.x = pk2(v[2 * j][0], v[2 * j][1]); o.y = pk2(v[2 * j][2], v[2 * j][3]); o.z = pk2(v[2 * j + 1][0], v[2 * j + 1][1]); o.w = pk2(v[2 * j + 1][2], v[2 * j + 1][3]);
;                 *(GAS v4u*)(HB + (size_t)m * D + 8 * lane + 512 * j) = o; }
;             float fl[8];
; #pragma unroll
;             for (int q = 0; q < 8; ++q) { float a = 0.f;
; #pragma unroll
;                 for (int j = 0; j < 4; ++j) { const f32x4 w = *(const LAS f32x4*)(wf + q * 1024 + P1COL(j)); a += (v[j][0] * w[0] + v[j][1] * w[1]) + (v[j][2] * w[2] + v[j][3] * w[3]); }
;                 fl[q] = wave_sum(a); }
;             float mine = fl[0];
; #pragma unroll
;             for (int q = 1; q < 8; ++q) mine = (lane == q) ? fl[q] : mine;
;             { const float z = mine + bfv; const float ls = fminf(z, 0.f) - log1pf(__expf(-fabsf(z)));
	v_mov_b32_e32 v31, v30
	v_mov_b32_e32 v22, v30
	s_nop 1
	v_permlane16_swap_b32_e32 v31, v22
	v_add_f32_e32 v22, v31, v22
	v_pk_add_f32 v[18:19], v[18:19], v[20:21]
	v_mov_b32_e32 v29, v28
	v_mov_b32_e32 v20, v28
	s_nop 1
	v_permlane16_swap_b32_e32 v29, v20
	v_add_f32_e32 v20, v29, v20
	v_add_f32_e32 v18, v18, v19
	v_mov_b32_e32 v94, v93
	v_mov_b32_e32 v24, v93
	s_nop 1
	v_permlane32_swap_b32_e32 v94, v24
	v_add_f32_e32 v24, v94, v24
	v_mov_b32_e32 v27, v26
	v_mov_b32_e32 v25, v26
	s_nop 1
	v_permlane32_swap_b32_e32 v27, v25
	v_add_f32_e32 v25, v27, v25
	s_waitcnt lgkmcnt(0)
	s_nop 1
	v_add_f32_dpp v18, v18, v18 quad_perm:[1,0,3,2] row_mask:0xf bank_mask:0xf
	s_waitcnt lgkmcnt(0)
	v_mov_b32_e32 v21, v20
	s_nop 1
	v_permlane32_swap_b32_e32 v21, v20
	v_add_f32_e32 v20, v21, v20
	s_waitcnt lgkmcnt(0)
	v_mov_b32_e32 v23, v22
	v_mov_b32_e32 v21, v22
	s_nop 1
	v_permlane32_swap_b32_e32 v23, v21
	v_add_f32_e32 v21, v23, v21
	v_cndmask_b32_e64 v22, v55, v74, s[4:5]
	v_cndmask_b32_e64 v22, v22, v75, s[6:7]
	s_waitcnt lgkmcnt(0)
	s_nop 1
	v_add_f32_dpp v18, v18, v18 quad_perm:[2,3,0,1] row_mask:0xf bank_mask:0xf
	v_cndmask_b32_e64 v22, v22, v92, s[8:9]
	v_cndmask_b32_e64 v22, v22, v24, s[10:11]
	v_cndmask_b32_e64 v22, v22, v25, s[12:13]
	v_cndmask_b32_e64 v20, v22, v20, s[14:15]
	s_waitcnt lgkmcnt(0)
	s_nop 1
	v_add_f32_dpp v18, v18, v18 row_half_mirror row_mask:0xf bank_mask:0xf
	v_cndmask_b32_e64 v20, v20, v21, s[16:17]
	v_add_f32_e32 v20, v71, v20
	v_min_f32_e32 v22, 0, v20
	v_mul_f32_e64 v20, |v20|, s29
	s_waitcnt lgkmcnt(0)
	s_nop 1
	v_add_f32_dpp v18, v18, v18 row_mirror row_mask:0xf bank_mask:0xf
	v_exp_f32_e32 v55, v20
	s_waitcnt lgkmcnt(0)
	v_mov_b32_e32 v19, v18
	s_nop 1
	v_permlane16_swap_b32_e32 v19, v18
	v_add_f32_e32 v18, v19, v18
	v_add_f32_e32 v92, 1.0, v55
	v_add_f32_e32 v23, -1.0, v92
	v_sub_f32_e32 v26, v23, v92
	v_add_f32_e32 v26, 1.0, v26
	s_waitcnt lgkmcnt(0)
	v_mov_b32_e32 v19, v18
	s_nop 1
	v_permlane32_swap_b32_e32 v19, v18
	v_add_f32_e32 v18, v19, v18
	v_fmamk_f32 v18, v18, 0x3a800000, v69
	v_mul_f32_e32 v19, 0x4f800000, v18
	v_cmp_gt_f32_e32 vcc, s45, v18
	v_sub_f32_e32 v23, v55, v23
	v_add_f32_e32 v23, v23, v26
	v_cndmask_b32_e32 v18, v18, v19, vcc
	v_sqrt_f32_e32 v19, v18
	s_nop 0
	v_add_u32_e32 v20, -1, v19
	v_fma_f32 v21, -v20, v19, v18
	v_cmp_ge_f32_e64 s[20:21], 0, v21
	v_add_u32_e32 v21, 1, v19
	s_nop 0
	v_cndmask_b32_e64 v20, v19, v20, s[20:21]
	v_fma_f32 v19, -v21, v19, v18
	v_cmp_lt_f32_e64 s[20:21], 0, v19
	s_nop 1
	v_cndmask_b32_e64 v19, v20, v21, s[20:21]
	v_mul_f32_e32 v20, 0x37800000, v19
	v_cndmask_b32_e32 v19, v19, v20, vcc
	v_cmp_class_f32_e32 vcc, v18, v70
	s_nop 1
	v_cndmask_b32_e32 v18, v19, v18, vcc
	v_div_scale_f32 v19, s[20:21], v18, v18, 1.0
	v_rcp_f32_e32 v20, v19
	s_lshl_b64 s[20:21], s[36:37], 11
	s_mov_b32 s37, 0x3f2aaaab
	s_mov_b32 s36, 0x3f317218
	v_fma_f32 v21, -v19, v20, 1.0
	v_fmac_f32_e32 v20, v21, v20
	v_div_scale_f32 v21, vcc, 1.0, v18, 1.0
	v_mul_f32_e32 v24, v21, v20
	v_fma_f32 v25, -v19, v24, v21
	v_fmac_f32_e32 v24, v25, v20
	v_fma_f32 v19, -v19, v24, v21
	v_div_fmas_f32 v19, v19, v20, v24
	v_div_fixup_f32 v18, v19, v18, 1.0
	v_pk_mul_f32 v[20:21], v[18:19], v[84:85] op_sel_hi:[0,1]
	v_pk_mul_f32 v[24:25], v[18:19], v[86:87] op_sel_hi:[0,1]
	v_pk_fma_f32 v[64:65], v[40:41], v[20:21], v[6:7]
	v_pk_mul_f32 v[20:21], v[18:19], v[80:81] op_sel_hi:[0,1]
	v_pk_fma_f32 v[62:63], v[38:39], v[24:25], v[8:9]
	v_pk_mul_f32 v[24:25], v[18:19], v[82:83] op_sel_hi:[0,1]
	v_pk_fma_f32 v[66:67], v[44:45], v[20:21], v[2:3]
	v_pk_mul_f32 v[20:21], v[18:19], v[76:77] op_sel_hi:[0,1]
	v_pk_fma_f32 v[32:33], v[42:43], v[24:25], v[4:5]
	v_pk_mul_f32 v[24:25], v[18:19], v[78:79] op_sel_hi:[0,1]
	v_pk_fma_f32 v[30:31], v[48:49], v[20:21], v[14:15]
	v_pk_mul_f32 v[20:21], v[18:19], v[88:89] op_sel_hi:[0,1]
	v_pk_mul_f32 v[18:19], v[18:19], v[90:91] op_sel_hi:[0,1]
	v_pk_fma_f32 v[28:29], v[46:47], v[24:25], v[16:17]
	v_pk_fma_f32 v[58:59], v[50:51], v[18:19], v[12:13]
	v_pk_fma_f32 v[60:61], v[52:53], v[20:21], v[10:11]
	v_lshl_add_u64 v[24:25], v[56:57], 0, s[20:21]
	v_cvt_pk_bf16_f32 v18, v64, v65
	v_cvt_pk_bf16_f32 v19, v62, v63
	v_cvt_pk_bf16_f32 v20, v66, v67
	v_cvt_pk_bf16_f32 v21, v32, v33
	global_store_dwordx4 v[24:25], v[18:21], off
	s_mov_b32 s20, 0x3e9b6dac
	s_nop 0
	v_cvt_pk_bf16_f32 v18, v30, v31
	v_cvt_pk_bf16_f32 v19, v28, v29
	v_cvt_pk_bf16_f32 v20, v60, v61
	v_cvt_pk_bf16_f32 v21, v58, v59
	ds_read_b128 v[74:77], v72
	ds_read_b128 v[78:81], v72 offset:16
	s_waitcnt lgkmcnt(1)
	v_mul_f32_e32 v26, v65, v75
	v_mul_f32_e32 v27, v63, v77
	v_fmac_f32_e32 v26, v64, v74
	v_fmac_f32_e32 v27, v62, v76
	ds_read_b128 v[74:77], v72 offset:2048
	v_add_f32_e32 v26, v26, v27
	s_waitcnt lgkmcnt(1)
	v_mul_f32_e32 v27, v67, v79
	v_mul_f32_e32 v56, v33, v81
	v_fmac_f32_e32 v27, v66, v78
	v_fmac_f32_e32 v56, v32, v80
	ds_read_b128 v[78:81], v72 offset:2064
	v_add_f32_e32 v26, 0, v26
	v_add_f32_e32 v27, v27, v56
	v_add_f32_e32 v26, v26, v27
	s_waitcnt lgkmcnt(1)
	v_mul_f32_e32 v27, v31, v75
	v_mul_f32_e32 v56, v29, v77
	v_fmac_f32_e32 v27, v30, v74
	v_fmac_f32_e32 v56, v28, v76
	v_add_f32_e32 v27, v27, v56
	v_add_f32_e32 v26, v26, v27
	s_waitcnt lgkmcnt(0)
	v_mul_f32_e32 v27, v61, v79
	v_mul_f32_e32 v56, v59, v81
	v_fmac_f32_e32 v27, v60, v78
	v_fmac_f32_e32 v56, v58, v80
	v_add_f32_e32 v27, v27, v56
	v_add_f32_e32 v56, v26, v27
	v_frexp_mant_f32_e32 v74, v92
	v_cmp_gt_f32_e32 vcc, s37, v74
	ds_read_b128 v[74:77], v72 offset:4096
	v_cvt_f64_f32_e32 v[26:27], v92
	s_waitcnt lgkmcnt(1)
	s_nop 1
	v_add_f32_dpp v57, v56, v56 quad_perm:[1,0,3,2] row_mask:0xf bank_mask:0xf
	v_frexp_exp_i32_f64_e32 v26, v[26:27]
	v_subbrev_co_u32_e32 v56, vcc, 0, v26, vcc
	v_sub_u32_e32 v27, 0, v56
	s_waitcnt lgkmcnt(0)
; #define LAS __attribute__((address_space(3)))
; template <int LO, int HI> __global__ void __launch_bounds__(NWAVES * 64, 2) fox_fwd(Args args) {
;     ...
;             for (int q = 0; q < 8; ++q) { float a = 0.f;
; #pragma unroll
;                 for (int j = 0; j < 4; ++j) { const f32x4 w = *(const LAS f32x4*)(wf + q * 1024 + P1COL(j)); a += (v[j][0] * w[0] + v[j][1] * w[1]) + (v[j][2] * w[2] + v[j][3] * w[3]); }
;                 fl[q] = wave_sum(a); }
;             float mine = fl[0];
; #pragma unroll
;             for (int q = 1; q < 8; ++q) mine = (lane == q) ? fl[q] : mine;
;             { const float z = mine + bfv; const float ls = fminf(z, 0.f) - log1pf(__expf(-fabsf(z)));
	s_nop 1
	v_add_f32_dpp v57, v57, v57 quad_perm:[2,3,0,1] row_mask:0xf bank_mask:0xf
	ds_read_b128 v[78:81], v72 offset:4112
	v_mul_f32_e32 v26, v65, v75
	v_fmac_f32_e32 v26, v64, v74
	v_mul_f32_e32 v74, v63, v77
	v_fmac_f32_e32 v74, v62, v76
	v_add_f32_e32 v26, v26, v74
	s_waitcnt lgkmcnt(0)
	v_mul_f32_e32 v79, v67, v79
	ds_read_b128 v[74:77], v72 offset:6144
	v_fmac_f32_e32 v79, v66, v78
	v_mul_f32_e32 v78, v33, v81
	v_fmac_f32_e32 v78, v32, v80
	v_add_f32_e32 v26, 0, v26
	v_add_f32_e32 v78, v79, v78
	v_add_f32_e32 v26, v26, v78
	ds_read_b128 v[78:81], v72 offset:6160
	s_waitcnt lgkmcnt(1)
	v_mul_f32_e32 v75, v31, v75
	v_fmac_f32_e32 v75, v30, v74
	v_mul_f32_e32 v74, v29, v77
	v_fmac_f32_e32 v74, v28, v76
	v_add_f32_e32 v74, v75, v74
	v_add_f32_e32 v26, v26, v74
	s_waitcnt lgkmcnt(0)
	v_mul_f32_e32 v74, v61, v79
	v_mul_f32_e32 v75, v59, v81
	v_fmac_f32_e32 v74, v60, v78
	v_fmac_f32_e32 v75, v58, v80
	v_add_f32_e32 v74, v74, v75
	v_add_f32_e32 v78, v26, v74
	ds_read_b128 v[74:77], v72 offset:8192
	v_ldexp_f32 v26, v92, v27
	s_waitcnt lgkmcnt(1)
	s_nop 1
	v_add_f32_dpp v83, v78, v78 quad_perm:[1,0,3,2] row_mask:0xf bank_mask:0xf
	ds_read_b128 v[78:81], v72 offset:8208
	s_waitcnt lgkmcnt(1)
	v_mul_f32_e32 v75, v65, v75
	v_fmac_f32_e32 v75, v64, v74
	v_mul_f32_e32 v74, v63, v77
	v_fmac_f32_e32 v74, v62, v76
	v_add_f32_e32 v74, v75, v74
	s_waitcnt lgkmcnt(0)
	v_mul_f32_e32 v79, v67, v79
	v_add_f32_e32 v85, 0, v74
	v_fmac_f32_e32 v79, v66, v78
	v_mul_f32_e32 v78, v33, v81
	ds_read_b128 v[74:77], v72 offset:10240
	v_fmac_f32_e32 v78, v32, v80
	v_add_f32_e32 v78, v79, v78
	v_add_f32_e32 v85, v85, v78
	ds_read_b128 v[78:81], v72 offset:10256
	s_waitcnt lgkmcnt(1)
	v_mul_f32_e32 v75, v31, v75
	v_fmac_f32_e32 v75, v30, v74
	v_mul_f32_e32 v74, v29, v77
	v_fmac_f32_e32 v74, v28, v76
	s_nop 1
	v_add_f32_dpp v57, v57, v57 row_half_mirror row_mask:0xf bank_mask:0xf
	v_add_f32_e32 v74, v75, v74
	s_waitcnt lgkmcnt(0)
	v_mul_f32_e32 v75, v61, v79
	v_mul_f32_e32 v76, v59, v81
	v_fmac_f32_e32 v75, v60, v78
	v_fmac_f32_e32 v76, v58, v80
	v_add_f32_e32 v74, v85, v74
	v_add_f32_e32 v75, v75, v76
	v_add_f32_e32 v74, v74, v75
	s_waitcnt lgkmcnt(0)
	s_nop 1
	v_add_f32_dpp v57, v57, v57 row_mirror row_mask:0xf bank_mask:0xf
	s_waitcnt lgkmcnt(0)
	s_nop 1
	v_add_f32_dpp v77, v83, v83 quad_perm:[2,3,0,1] row_mask:0xf bank_mask:0xf
	s_waitcnt lgkmcnt(0)
	s_nop 1
	v_add_f32_dpp v74, v74, v74 quad_perm:[1,0,3,2] row_mask:0xf bank_mask:0xf
	s_waitcnt lgkmcnt(0)
	v_mov_b32_e32 v76, v57
	s_nop 1
	v_permlane16_swap_b32_e32 v76, v57
	v_add_f32_e32 v57, v76, v57
	s_waitcnt lgkmcnt(0)
	s_nop 1
	v_add_f32_dpp v78, v77, v77 row_half_mirror row_mask:0xf bank_mask:0xf
	s_waitcnt lgkmcnt(0)
	s_nop 1
	v_add_f32_dpp v80, v74, v74 quad_perm:[2,3,0,1] row_mask:0xf bank_mask:0xf
	s_waitcnt lgkmcnt(0)
	v_mov_b32_e32 v76, v57
	s_nop 1
	v_permlane32_swap_b32_e32 v76, v57
	v_add_f32_e32 v57, v76, v57
	ds_read_b128 v[74:77], v72 offset:12288
	s_waitcnt lgkmcnt(1)
	s_nop 1
	v_add_f32_dpp v82, v78, v78 row_mirror row_mask:0xf bank_mask:0xf
	s_waitcnt lgkmcnt(1)
	s_nop 1
	v_add_f32_dpp v84, v80, v80 row_half_mirror row_mask:0xf bank_mask:0xf
	ds_read_b128 v[78:81], v72 offset:12304
	s_waitcnt lgkmcnt(1)
	v_mul_f32_e32 v75, v65, v75
	v_fmac_f32_e32 v75, v64, v74
	v_mul_f32_e32 v74, v63, v77
	v_fmac_f32_e32 v74, v62, v76
	v_add_f32_e32 v74, v75, v74
	s_waitcnt lgkmcnt(0)
	v_mul_f32_e32 v79, v67, v79
	v_add_f32_e32 v85, 0, v74
	v_fmac_f32_e32 v79, v66, v78
	v_mul_f32_e32 v78, v33, v81
	ds_read_b128 v[74:77], v72 offset:14336
	v_fmac_f32_e32 v78, v32, v80
	v_add_f32_e32 v78, v79, v78
	v_add_f32_e32 v85, v85, v78
	ds_read_b128 v[78:81], v72 offset:14352
	s_waitcnt lgkmcnt(1)
	v_mul_f32_e32 v75, v31, v75
	v_fmac_f32_e32 v75, v30, v74
	v_mul_f32_e32 v74, v29, v77
	v_fmac_f32_e32 v74, v28, v76
	v_add_f32_e32 v74, v75, v74
	s_waitcnt lgkmcnt(0)
	v_mul_f32_e32 v79, v61, v79
	v_add_f32_e32 v85, v85, v74
	v_fmac_f32_e32 v79, v60, v78
	v_mul_f32_e32 v78, v59, v81
	ds_read_b128 v[74:77], v72 offset:16384
	v_fmac_f32_e32 v78, v58, v80
	v_add_f32_e32 v78, v79, v78
	v_add_f32_e32 v85, v85, v78
	ds_read_b128 v[78:81], v72 offset:16400
	s_waitcnt lgkmcnt(1)
	v_mul_f32_e32 v75, v65, v75
	v_fmac_f32_e32 v75, v64, v74
	v_mul_f32_e32 v74, v63, v77
	v_fmac_f32_e32 v74, v62, v76
	v_add_f32_e32 v74, v75, v74
	s_waitcnt lgkmcnt(0)
	v_mul_f32_e32 v79, v67, v79
	v_add_f32_e32 v87, 0, v74
	v_fmac_f32_e32 v79, v66, v78
	v_mul_f32_e32 v78, v33, v81
	ds_read_b128 v[74:77], v72 offset:18432
	v_fmac_f32_e32 v78, v32, v80
	v_add_f32_e32 v78, v79, v78
	v_add_f32_e32 v87, v87, v78
	ds_read_b128 v[78:81], v72 offset:18448
	s_waitcnt lgkmcnt(1)
	v_mul_f32_e32 v75, v31, v75
	v_fmac_f32_e32 v75, v30, v74
	v_mul_f32_e32 v74, v29, v77
	v_fmac_f32_e32 v74, v28, v76
	v_add_f32_e32 v74, v75, v74
	s_waitcnt lgkmcnt(0)
	v_mul_f32_e32 v75, v61, v79
	v_mul_f32_e32 v76, v59, v81
	v_fmac_f32_e32 v75, v60, v78
	v_fmac_f32_e32 v76, v58, v80
	v_add_f32_e32 v74, v87, v74
	v_add_f32_e32 v75, v75, v76
	v_add_f32_e32 v74, v74, v75
	s_waitcnt lgkmcnt(0)
	s_nop 1
	v_add_f32_dpp v77, v85, v85 quad_perm:[1,0,3,2] row_mask:0xf bank_mask:0xf
	s_waitcnt lgkmcnt(0)
	s_nop 1
	v_add_f32_dpp v74, v74, v74 quad_perm:[1,0,3,2] row_mask:0xf bank_mask:0xf
	s_waitcnt lgkmcnt(0)
	s_nop 1
	v_add_f32_dpp v76, v84, v84 row_mirror row_mask:0xf bank_mask:0xf
	s_waitcnt lgkmcnt(0)
	v_mov_b32_e32 v83, v82
	v_mov_b32_e32 v79, v82
	s_nop 1
	v_permlane16_swap_b32_e32 v83, v79
	v_add_f32_e32 v79, v83, v79
	s_waitcnt lgkmcnt(0)
	s_nop 1
	v_add_f32_dpp v77, v77, v77 quad_perm:[2,3,0,1] row_mask:0xf bank_mask:0xf
	s_waitcnt lgkmcnt(0)
; #define LAS __attribute__((address_space(3)))
; template <int LO, int HI> __global__ void __launch_bounds__(NWAVES * 64, 2) fox_fwd(Args args) {
;     ...
;             for (int q = 0; q < 8; ++q) { float a = 0.f;
; #pragma unroll
;                 for (int j = 0; j < 4; ++j) { const f32x4 w = *(const LAS f32x4*)(wf + q * 1024 + P1COL(j)); a += (v[j][0] * w[0] + v[j][1] * w[1]) + (v[j][2] * w[2] + v[j][3] * w[3]); }
;                 fl[q] = wave_sum(a); }
	s_nop 1
	v_add_f32_dpp v74, v74, v74 quad_perm:[2,3,0,1] row_mask:0xf bank_mask:0xf
	s_waitcnt lgkmcnt(0)
	v_mov_b32_e32 v80, v76
	s_nop 1
	v_permlane16_swap_b32_e32 v80, v76
	v_add_f32_e32 v76, v80, v76
	s_waitcnt lgkmcnt(0)
	s_nop 1
	v_add_f32_dpp v77, v77, v77 row_half_mirror row_mask:0xf bank_mask:0xf
	s_waitcnt lgkmcnt(0)
	s_nop 1
	v_add_f32_dpp v75, v74, v74 row_half_mirror row_mask:0xf bank_mask:0xf
	s_waitcnt lgkmcnt(0)
	v_mov_b32_e32 v81, v79
	v_mov_b32_e32 v74, v79
	s_nop 1
	v_permlane32_swap_b32_e32 v81, v74
	v_add_f32_e32 v74, v81, v74
	s_waitcnt lgkmcnt(0)
	s_nop 1
	v_add_f32_dpp v77, v77, v77 row_mirror row_mask:0xf bank_mask:0xf
	s_waitcnt lgkmcnt(0)
	s_nop 1
	v_add_f32_dpp v79, v75, v75 row_mirror row_mask:0xf bank_mask:0xf
	v_mov_b32_e32 v82, v76
	v_mov_b32_e32 v75, v76
	s_nop 1
	v_permlane32_swap_b32_e32 v82, v75
	v_add_f32_e32 v75, v82, v75
	ds_read_b128 v[80:83], v72 offset:20480
	s_waitcnt lgkmcnt(1)
	v_mov_b32_e32 v78, v77
	v_mov_b32_e32 v76, v77
	s_nop 1
	v_permlane16_swap_b32_e32 v78, v76
	v_add_f32_e32 v76, v78, v76
	s_waitcnt lgkmcnt(1)
	v_mov_b32_e32 v84, v79
	v_mov_b32_e32 v78, v79
	s_nop 1
	v_permlane16_swap_b32_e32 v84, v78
	v_add_f32_e32 v78, v84, v78
	ds_read_b128 v[84:87], v72 offset:20496
	s_waitcnt lgkmcnt(1)
	v_mul_f32_e32 v81, v65, v81
	v_fmac_f32_e32 v81, v64, v80
	v_mul_f32_e32 v80, v63, v83
	v_fmac_f32_e32 v80, v62, v82
	v_add_f32_e32 v80, v81, v80
	s_waitcnt lgkmcnt(0)
	v_mul_f32_e32 v85, v67, v85
	v_add_f32_e32 v88, 0, v80
	v_fmac_f32_e32 v85, v66, v84
	v_mul_f32_e32 v84, v33, v87
	ds_read_b128 v[80:83], v72 offset:22528
	v_fmac_f32_e32 v84, v32, v86
	v_add_f32_e32 v84, v85, v84
	v_add_f32_e32 v88, v88, v84
	ds_read_b128 v[84:87], v72 offset:22544
	s_waitcnt lgkmcnt(1)
	v_mul_f32_e32 v81, v31, v81
	v_fmac_f32_e32 v81, v30, v80
	v_mul_f32_e32 v80, v29, v83
	v_fmac_f32_e32 v80, v28, v82
	v_add_f32_e32 v80, v81, v80
	s_waitcnt lgkmcnt(0)
	v_mul_f32_e32 v81, v61, v85
	v_fmac_f32_e32 v81, v60, v84
	ds_read_b128 v[82:85], v72 offset:24576
	v_mul_f32_e32 v87, v59, v87
	v_fmac_f32_e32 v87, v58, v86
	v_add_f32_e32 v80, v88, v80
	v_add_f32_e32 v81, v81, v87
	ds_read_b128 v[86:89], v72 offset:24592
	s_waitcnt lgkmcnt(1)
	v_pk_mul_f32 v[82:83], v[64:65], v[82:83]
	v_pk_mul_f32 v[84:85], v[62:63], v[84:85]
	v_add_f32_e32 v80, v80, v81
	v_pk_mov_b32 v[90:91], v[82:83], v[84:85] op_sel:[1,0]
	v_mov_b32_e32 v83, v85
	v_pk_add_f32 v[82:83], v[90:91], v[82:83]
	s_waitcnt lgkmcnt(0)
	v_pk_mul_f32 v[86:87], v[66:67], v[86:87]
	v_add_f32_e32 v82, v82, v83
	v_add_f32_e32 v94, 0, v82
	ds_read_b128 v[82:85], v72 offset:26624
	ds_read_b128 v[90:93], v72 offset:26640
	v_pk_mul_f32 v[88:89], v[32:33], v[88:89]
	v_pk_mov_b32 v[96:97], v[86:87], v[88:89] op_sel:[1,0]
	v_mov_b32_e32 v87, v89
	v_pk_add_f32 v[86:87], v[96:97], v[86:87]
	s_waitcnt lgkmcnt(0)
	v_mul_f32_e32 v88, v61, v91
	v_pk_add_f32 v[86:87], v[86:87], v[86:87] op_sel:[0,1] op_sel_hi:[1,0]
	v_mul_f32_e32 v95, v60, v90
	v_mov_b32_e32 v87, v88
	v_pk_add_f32 v[88:89], v[94:95], v[86:87]
	v_mul_f32_e32 v86, v31, v83
	v_pk_fma_f32 v[82:83], v[30:31], v[82:83], v[86:87] op_sel_hi:[1,1,0]
	v_mul_f32_e32 v86, v29, v85
	v_mul_f32_e32 v90, v58, v92
	v_mul_f32_e32 v91, v59, v93
	v_pk_fma_f32 v[84:85], v[28:29], v[84:85], v[86:87] op_sel_hi:[1,1,0]
	v_mov_b32_e32 v83, v90
	v_mov_b32_e32 v85, v91
	v_pk_add_f32 v[82:83], v[82:83], v[84:85]
	ds_read_b128 v[84:87], v72 offset:28672
	v_pk_add_f32 v[82:83], v[88:89], v[82:83]
	ds_read_b128 v[88:91], v72 offset:28688
	v_add_f32_e32 v82, v82, v83
	s_waitcnt lgkmcnt(1)
	v_pk_mul_f32 v[64:65], v[64:65], v[84:85]
	v_pk_mul_f32 v[62:63], v[62:63], v[86:87]
	s_waitcnt lgkmcnt(0)
	v_pk_mul_f32 v[66:67], v[66:67], v[88:89]
	v_pk_mov_b32 v[84:85], v[64:65], v[62:63] op_sel:[1,0]
	v_mov_b32_e32 v65, v63
	v_pk_add_f32 v[62:63], v[84:85], v[64:65]
	v_pk_mul_f32 v[32:33], v[32:33], v[90:91]
	v_add_f32_e32 v62, v62, v63
	v_add_f32_e32 v92, 0, v62
	ds_read_b128 v[62:65], v72 offset:30720
	ds_read_b128 v[84:87], v72 offset:30736
	v_pk_mov_b32 v[88:89], v[66:67], v[32:33] op_sel:[1,0]
	v_mov_b32_e32 v67, v33
	v_pk_add_f32 v[32:33], v[88:89], v[66:67]
	s_waitcnt lgkmcnt(0)
	v_mul_f32_e32 v93, v60, v84
	v_mul_f32_e32 v60, v61, v85
	v_mul_f32_e32 v61, v58, v86
	v_mul_f32_e32 v59, v59, v87
	v_mul_f32_e32 v58, v31, v63
	v_pk_fma_f32 v[30:31], v[30:31], v[62:63], v[58:59] op_sel_hi:[1,1,0]
	v_mul_f32_e32 v58, v29, v65
	v_pk_add_f32 v[32:33], v[32:33], v[32:33] op_sel:[0,1] op_sel_hi:[1,0]
	v_pk_fma_f32 v[28:29], v[28:29], v[64:65], v[58:59] op_sel_hi:[1,1,0]
	v_mov_b32_e32 v33, v60
	v_mov_b32_e32 v31, v61
	v_mov_b32_e32 v29, v59
	v_pk_add_f32 v[32:33], v[92:93], v[32:33]
	v_pk_add_f32 v[28:29], v[30:31], v[28:29]
	s_nop 1
	v_add_f32_dpp v30, v80, v80 quad_perm:[1,0,3,2] row_mask:0xf bank_mask:0xf
	v_pk_add_f32 v[28:29], v[32:33], v[28:29]
	v_add_f32_e32 v28, v28, v29
	s_nop 1
	v_add_f32_dpp v32, v82, v82 quad_perm:[1,0,3,2] row_mask:0xf bank_mask:0xf
	s_waitcnt lgkmcnt(0)
	s_nop 1
	v_add_f32_dpp v30, v30, v30 quad_perm:[2,3,0,1] row_mask:0xf bank_mask:0xf
	s_waitcnt lgkmcnt(0)
	s_nop 1
	v_add_f32_dpp v28, v28, v28 quad_perm:[1,0,3,2] row_mask:0xf bank_mask:0xf
	s_waitcnt lgkmcnt(0)
	s_nop 1
	v_add_f32_dpp v32, v32, v32 quad_perm:[2,3,0,1] row_mask:0xf bank_mask:0xf
	s_waitcnt lgkmcnt(0)
	s_nop 1
	v_add_f32_dpp v30, v30, v30 row_half_mirror row_mask:0xf bank_mask:0xf
	s_waitcnt lgkmcnt(0)
	s_nop 1
	v_add_f32_dpp v28, v28, v28 quad_perm:[2,3,0,1] row_mask:0xf bank_mask:0xf
	s_waitcnt lgkmcnt(0)
	s_nop 1
	v_add_f32_dpp v32, v32, v32 row_half_mirror row_mask:0xf bank_mask:0xf
	s_waitcnt lgkmcnt(0)
	s_nop 1
	v_add_f32_dpp v30, v30, v30 row_mirror row_mask:0xf bank_mask:0xf
	s_waitcnt lgkmcnt(0)
; #define LAS __attribute__((address_space(3)))
; __device__ __forceinline__ float wave_sum(float v) {
; #pragma unroll
;     for (int o = 1; o < 64; o <<= 1) v += __shfl_xor(v, o);
;     return v;
; }
; template <int LO, int HI> __global__ void __launch_bounds__(NWAVES * 64, 2) fox_fwd(Args args) {
;     ...
;             for (int q = 0; q < 8; ++q) { float a = 0.f;
; #pragma unroll
;                 for (int j = 0; j < 4; ++j) { const f32x4 w = *(const LAS f32x4*)(wf + q * 1024 + P1COL(j)); a += (v[j][0] * w[0] + v[j][1] * w[1]) + (v[j][2] * w[2] + v[j][3] * w[3]); }
;                 fl[q] = wave_sum(a); }
;             float mine = fl[0];
; #pragma unroll
;             for (int q = 1; q < 8; ++q) mine = (lane == q) ? fl[q] : mine;
	s_nop 1
	v_add_f32_dpp v28, v28, v28 row_half_mirror row_mask:0xf bank_mask:0xf
	s_waitcnt lgkmcnt(0)
	s_nop 1
	v_add_f32_dpp v32, v32, v32 row_mirror row_mask:0xf bank_mask:0xf
	s_waitcnt lgkmcnt(0)
	v_mov_b32_e32 v31, v30
	s_nop 1
	v_permlane16_swap_b32_e32 v31, v30
	v_add_f32_e32 v30, v31, v30
	s_waitcnt lgkmcnt(0)
	s_nop 1
	v_add_f32_dpp v28, v28, v28 row_mirror row_mask:0xf bank_mask:0xf
	s_waitcnt lgkmcnt(0)
	v_mov_b32_e32 v33, v32
	s_nop 1
	v_permlane16_swap_b32_e32 v33, v32
	v_add_f32_e32 v32, v33, v32
	v_mov_b32_e32 v77, v76
	v_mov_b32_e32 v58, v76
	s_nop 1
	v_permlane32_swap_b32_e32 v77, v58
	v_add_f32_e32 v58, v77, v58
	s_waitcnt lgkmcnt(0)
	v_mov_b32_e32 v29, v28
	s_nop 1
	v_permlane16_swap_b32_e32 v29, v28
	v_add_f32_e32 v28, v29, v28
	v_mov_b32_e32 v79, v78
	v_mov_b32_e32 v59, v78
	s_nop 1
	v_permlane32_swap_b32_e32 v79, v59
	v_add_f32_e32 v59, v79, v59
	s_waitcnt lgkmcnt(0)
	v_mov_b32_e32 v31, v30
	s_nop 1
	v_permlane32_swap_b32_e32 v31, v30
	v_add_f32_e32 v30, v31, v30
	s_waitcnt lgkmcnt(0)
	v_mov_b32_e32 v33, v32
	v_mov_b32_e32 v31, v32
	s_nop 1
	v_permlane32_swap_b32_e32 v33, v31
	v_add_f32_e32 v31, v33, v31
	global_store_dwordx4 v[24:25], v[18:21], off offset:1024
	s_waitcnt lgkmcnt(0)
	v_mov_b32_e32 v29, v28
	s_nop 1
	v_permlane32_swap_b32_e32 v29, v28
	v_add_f32_e32 v28, v29, v28
	v_cndmask_b32_e64 v29, v57, v74, s[4:5]
	v_cndmask_b32_e64 v29, v29, v75, s[6:7]
	v_cndmask_b32_e64 v29, v29, v58, s[8:9]
	v_cndmask_b32_e64 v29, v29, v59, s[10:11]
	v_cndmask_b32_e64 v29, v29, v30, s[12:13]
	v_cndmask_b32_e64 v29, v29, v31, s[14:15]
	v_cndmask_b32_e64 v28, v29, v28, s[16:17]
	v_add_f32_e32 v29, v71, v28
	v_mul_f32_e64 v28, |v29|, s29
	v_exp_f32_e32 v78, v28
	v_ldexp_f32 v28, v23, v27
	v_min_f32_e32 v23, 0, v29
	v_add_f32_e32 v20, 1.0, v78
	v_add_f32_e32 v18, -1.0, v20
	v_sub_f32_e32 v19, v18, v20
	v_add_f32_e32 v19, 1.0, v19
	v_sub_f32_e32 v18, v78, v18
	v_add_f32_e32 v21, v18, v19
	v_frexp_mant_f32_e32 v24, v20
	v_cvt_f64_f32_e32 v[18:19], v20
	v_frexp_exp_i32_f64_e32 v18, v[18:19]
	v_cmp_gt_f32_e32 vcc, s37, v24
	s_nop 1
	v_subbrev_co_u32_e32 v57, vcc, 0, v18, vcc
	v_sub_u32_e32 v18, 0, v57
	v_ldexp_f32 v27, v20, v18
	v_ldexp_f32 v29, v21, v18
	v_pk_add_f32 v[18:19], v[26:27], 1.0 op_sel_hi:[1,0]
	v_pk_add_f32 v[32:33], v[26:27], -1.0 op_sel_hi:[1,0]
	v_pk_add_f32 v[20:21], v[18:19], -1.0 op_sel_hi:[1,0]
	v_pk_add_f32 v[58:59], v[32:33], 1.0 op_sel_hi:[1,0]
	v_pk_add_f32 v[20:21], v[26:27], v[20:21] neg_lo:[0,1] neg_hi:[0,1]
	v_pk_add_f32 v[26:27], v[26:27], v[58:59] neg_lo:[0,1] neg_hi:[0,1]
	v_pk_add_f32 v[20:21], v[28:29], v[20:21]
	v_pk_add_f32 v[26:27], v[28:29], v[26:27]
	v_pk_add_f32 v[24:25], v[18:19], v[20:21]
	v_pk_add_f32 v[28:29], v[32:33], v[26:27]
	v_rcp_f32_e32 v30, v24
	v_rcp_f32_e32 v31, v25
	v_pk_add_f32 v[18:19], v[24:25], v[18:19] neg_lo:[0,1] neg_hi:[0,1]
	v_pk_add_f32 v[32:33], v[28:29], v[32:33] neg_lo:[0,1] neg_hi:[0,1]
	v_pk_add_f32 v[18:19], v[20:21], v[18:19] neg_lo:[0,1] neg_hi:[0,1]
	v_pk_mul_f32 v[20:21], v[28:29], v[30:31]
	v_pk_add_f32 v[26:27], v[26:27], v[32:33] neg_lo:[0,1] neg_hi:[0,1]
	v_pk_mul_f32 v[32:33], v[24:25], v[20:21]
	v_cmp_neq_f32_e32 vcc, s46, v55
	v_pk_fma_f32 v[58:59], v[20:21], v[24:25], v[32:33] neg_lo:[0,0,1] neg_hi:[0,0,1]
	s_nop 0
	v_pk_fma_f32 v[58:59], v[20:21], v[18:19], v[58:59]
	s_nop 0
	v_pk_add_f32 v[60:61], v[32:33], v[58:59]
	s_nop 0
	v_pk_add_f32 v[62:63], v[28:29], v[60:61] neg_lo:[0,1] neg_hi:[0,1]
	v_pk_add_f32 v[32:33], v[60:61], v[32:33] neg_lo:[0,1] neg_hi:[0,1]
	v_pk_add_f32 v[28:29], v[28:29], v[62:63] neg_lo:[0,1] neg_hi:[0,1]
	s_nop 0
	v_pk_add_f32 v[28:29], v[28:29], v[60:61] neg_lo:[0,1] neg_hi:[0,1]
	s_nop 0
	v_pk_add_f32 v[26:27], v[26:27], v[28:29]
	v_pk_add_f32 v[28:29], v[32:33], v[58:59] neg_lo:[0,1] neg_hi:[0,1]
	s_nop 0
	v_pk_add_f32 v[26:27], v[28:29], v[26:27]
	s_nop 0
	v_pk_add_f32 v[28:29], v[62:63], v[26:27]
	s_nop 0
	v_pk_mul_f32 v[32:33], v[30:31], v[28:29]
	s_nop 0
	v_pk_mul_f32 v[58:59], v[24:25], v[32:33]
	s_nop 0
	v_pk_fma_f32 v[24:25], v[32:33], v[24:25], v[58:59] neg_lo:[0,0,1] neg_hi:[0,0,1]
	s_nop 0
	v_pk_fma_f32 v[18:19], v[32:33], v[18:19], v[24:25]
	v_pk_add_f32 v[24:25], v[62:63], v[28:29] neg_lo:[0,1] neg_hi:[0,1]
	s_nop 0
	v_pk_add_f32 v[24:25], v[26:27], v[24:25]
	v_pk_add_f32 v[26:27], v[58:59], v[18:19]
	s_nop 0
	v_pk_add_f32 v[60:61], v[28:29], v[26:27] neg_lo:[0,1] neg_hi:[0,1]
	v_pk_add_f32 v[58:59], v[26:27], v[58:59] neg_lo:[0,1] neg_hi:[0,1]
	v_pk_add_f32 v[28:29], v[28:29], v[60:61] neg_lo:[0,1] neg_hi:[0,1]
	v_pk_add_f32 v[18:19], v[58:59], v[18:19] neg_lo:[0,1] neg_hi:[0,1]
	v_pk_add_f32 v[26:27], v[28:29], v[26:27] neg_lo:[0,1] neg_hi:[0,1]
	s_nop 0
	v_pk_add_f32 v[24:25], v[24:25], v[26:27]
	s_nop 0
	v_pk_add_f32 v[18:19], v[18:19], v[24:25]
	v_pk_add_f32 v[24:25], v[20:21], v[32:33]
	v_pk_add_f32 v[18:19], v[60:61], v[18:19]
	v_pk_add_f32 v[20:21], v[24:25], v[20:21] neg_lo:[0,1] neg_hi:[0,1]
	v_pk_mul_f32 v[18:19], v[30:31], v[18:19]
	v_pk_add_f32 v[20:21], v[32:33], v[20:21] neg_lo:[0,1] neg_hi:[0,1]
	v_cvt_f32_i32_e32 v32, v56
	v_pk_add_f32 v[18:19], v[20:21], v[18:19]
	v_cvt_f32_i32_e32 v33, v57
	v_pk_add_f32 v[26:27], v[24:25], v[18:19]
	s_nop 0
	v_pk_add_f32 v[20:21], v[26:27], v[24:25] neg_lo:[0,1] neg_hi:[0,1]
	v_pk_mul_f32 v[28:29], v[26:27], v[26:27]
	v_pk_add_f32 v[18:19], v[18:19], v[20:21] neg_lo:[0,1] neg_hi:[0,1]
	v_mov_b32_e32 v20, 0x3ecc95a3
	v_pk_fma_f32 v[30:31], v[28:29], s[20:21], v[20:21] op_sel_hi:[1,0,0]
	s_mov_b32 s20, 0x3f2aaada
	v_ldexp_f32 v24, v26, 1
	v_pk_fma_f32 v[30:31], v[28:29], v[30:31], s[20:21] op_sel_hi:[1,1,0]
	v_ldexp_f32 v25, v27, 1
	v_pk_mul_f32 v[26:27], v[26:27], v[28:29]
; #define LAS __attribute__((address_space(3)))
; template <int LO, int HI> __global__ void __launch_bounds__(NWAVES * 64, 2) fox_fwd(Args args) {
;     ...
;             for (int q = 0; q < 8; ++q) { float a = 0.f;
; #pragma unroll
;                 for (int j = 0; j < 4; ++j) { const f32x4 w = *(const LAS f32x4*)(wf + q * 1024 + P1COL(j)); a += (v[j][0] * w[0] + v[j][1] * w[1]) + (v[j][2] * w[2] + v[j][3] * w[3]); }
;     ...
;             { const float z = mine + bfv; const float ls = fminf(z, 0.f) - log1pf(__expf(-fabsf(z)));
; #pragma unroll
;               for (int k = 0; k < 4; ++k)
; #pragma unroll
;                   for (int e = 0; e < 4; ++e) lsq[k][e] = (r == 4 * k + e) ? ls : lsq[k][e]; }
	v_pk_mul_f32 v[28:29], v[32:33], s[36:37] op_sel_hi:[1,0]
	v_pk_mul_f32 v[26:27], v[26:27], v[30:31]
	v_pk_fma_f32 v[58:59], v[32:33], s[36:37], v[28:29] op_sel_hi:[1,0,1] neg_lo:[0,0,1] neg_hi:[0,0,1]
	v_pk_add_f32 v[30:31], v[24:25], v[26:27]
	s_mov_b32 s20, 0xb102e308
	v_pk_add_f32 v[24:25], v[30:31], v[24:25] neg_lo:[0,1] neg_hi:[0,1]
	v_ldexp_f32 v57, v19, 1
	v_pk_fma_f32 v[32:33], v[32:33], s[20:21], v[58:59] op_sel_hi:[1,0,1]
	v_pk_add_f32 v[24:25], v[26:27], v[24:25] neg_lo:[0,1] neg_hi:[0,1]
	v_ldexp_f32 v18, v18, 1
	v_mov_b32_e32 v26, v28
	v_mov_b32_e32 v27, v25
	v_mov_b32_e32 v56, v32
	v_mov_b32_e32 v19, v57
	v_pk_add_f32 v[26:27], v[26:27], v[56:57]
	v_pk_add_f32 v[56:57], v[18:19], v[24:25]
	v_mov_b32_e32 v25, v31
	v_mov_b32_e32 v19, v57
	v_pk_add_f32 v[58:59], v[28:29], v[32:33]
	v_pk_add_f32 v[18:19], v[18:19], v[24:25]
	v_pk_add_f32 v[24:25], v[30:31], v[56:57]
	v_mov_b32_e32 v74, v30
	v_pk_add_f32 v[60:61], v[58:59], v[24:25]
	v_mov_b32_e32 v66, v24
	v_mov_b32_e32 v67, v61
	v_mov_b32_e32 v75, v59
	v_pk_add_f32 v[66:67], v[66:67], v[74:75] neg_lo:[0,1] neg_hi:[0,1]
	v_mov_b32_e32 v62, v60
	v_mov_b32_e32 v63, v59
	v_mov_b32_e32 v64, v58
	v_mov_b32_e32 v65, v29
	v_mov_b32_e32 v74, v58
	v_mov_b32_e32 v75, v61
	v_mov_b32_e32 v29, v67
	v_pk_add_f32 v[62:63], v[62:63], v[64:65] neg_lo:[0,1] neg_hi:[0,1]
	v_mov_b32_e32 v64, v24
	v_mov_b32_e32 v65, v33
	v_pk_add_f32 v[28:29], v[74:75], v[28:29] neg_lo:[0,1] neg_hi:[0,1]
	v_pk_add_f32 v[64:65], v[64:65], v[62:63] neg_lo:[0,1] neg_hi:[0,1]
	v_mov_b32_e32 v74, v28
	v_mov_b32_e32 v75, v63
	v_mov_b32_e32 v76, v60
	v_mov_b32_e32 v77, v25
	v_mov_b32_e32 v63, v31
	v_pk_add_f32 v[74:75], v[32:33], v[74:75] neg_lo:[0,1] neg_hi:[0,1]
	v_pk_add_f32 v[62:63], v[76:77], v[62:63] neg_lo:[0,1] neg_hi:[0,1]
	v_mov_b32_e32 v33, v59
	v_pk_add_f32 v[26:27], v[26:27], v[62:63] neg_lo:[0,1] neg_hi:[0,1]
	v_pk_add_f32 v[28:29], v[32:33], v[28:29] neg_lo:[0,1] neg_hi:[0,1]
	v_pk_add_f32 v[18:19], v[18:19], v[66:67] neg_lo:[0,1] neg_hi:[0,1]
	v_pk_add_f32 v[24:25], v[24:25], v[30:31] neg_lo:[0,1] neg_hi:[0,1]
	v_pk_add_f32 v[30:31], v[18:19], v[28:29]
	v_mov_b32_e32 v29, v65
	v_mov_b32_e32 v19, v27
	v_pk_add_f32 v[32:33], v[64:65], v[26:27]
	v_pk_add_f32 v[18:19], v[28:29], v[18:19]
	v_mov_b32_e32 v26, v30
	v_pk_add_f32 v[18:19], v[18:19], v[74:75] neg_lo:[0,1] neg_hi:[0,1]
	v_mov_b32_e32 v27, v33
	v_pk_add_f32 v[24:25], v[56:57], v[24:25] neg_lo:[0,1] neg_hi:[0,1]
	v_pk_add_f32 v[26:27], v[26:27], v[18:19] neg_lo:[0,1] neg_hi:[0,1]
	v_pk_add_f32 v[18:19], v[24:25], v[18:19] neg_lo:[0,1] neg_hi:[0,1]
	v_pk_add_f32 v[26:27], v[28:29], v[26:27] neg_lo:[0,1] neg_hi:[0,1]
	v_pk_add_f32 v[24:25], v[32:33], v[30:31]
	v_pk_add_f32 v[18:19], v[18:19], v[26:27]
	v_pk_add_f32 v[26:27], v[60:61], v[24:25]
	v_mov_b32_e32 v64, 0x7f800000
	v_pk_add_f32 v[28:29], v[26:27], v[60:61] neg_lo:[0,1] neg_hi:[0,1]
	v_mov_b32_e32 v65, 0x7fc00000
	v_pk_add_f32 v[24:25], v[24:25], v[28:29] neg_lo:[0,1] neg_hi:[0,1]
	v_mov_b32_e32 v66, 0xff800000
	v_pk_add_f32 v[18:19], v[18:19], v[24:25]
	s_add_u32 s20, s26, s34
	v_pk_add_f32 v[18:19], v[26:27], v[18:19]
	s_addc_u32 s21, s27, s35
	v_cndmask_b32_e32 v18, v64, v18, vcc
	v_cmp_neq_f32_e32 vcc, s46, v78
	s_mov_b64 s[34:35], 0x2000
	v_mov_b32_e32 v58, 0x3f317218
	v_cndmask_b32_e32 v19, v64, v19, vcc
	v_cmp_ngt_f32_e32 vcc, -1.0, v78
	v_mov_b32_e32 v21, v37
	v_mov_b32_e32 v30, v37
	v_cndmask_b32_e32 v19, v65, v19, vcc
	v_cmp_ngt_f32_e32 vcc, -1.0, v55
	v_mov_b32_e32 v31, v37
	v_mov_b32_e32 v32, v37
	v_cndmask_b32_e32 v18, v65, v18, vcc
	v_cmp_neq_f32_e32 vcc, -1.0, v55
	v_mov_b32_e32 v33, v37
	v_mov_b32_e32 v26, v37
	v_cndmask_b32_e32 v18, v66, v18, vcc
	v_cmp_neq_f32_e32 vcc, -1.0, v78
	v_mov_b32_e32 v27, v37
	v_mov_b32_e32 v28, v37
	v_cndmask_b32_e32 v19, v66, v19, vcc
	v_cmp_lt_f32_e64 vcc, |v78|, s47
	v_mov_b32_e32 v29, v37
	v_mov_b32_e32 v24, v37
	v_cndmask_b32_e32 v19, v19, v78, vcc
	v_cmp_lt_f32_e64 vcc, |v55|, s47
	v_mov_b32_e32 v25, v37
	s_nop 0
	v_cndmask_b32_e32 v18, v18, v55, vcc
	v_pk_add_f32 v[18:19], v[22:23], v[18:19] neg_lo:[0,1] neg_hi:[0,1]
	v_mov_b32_e32 v55, v37
	v_lshl_add_u64 v[22:23], s[20:21], 0, v[36:37]
	s_mov_b64 s[20:21], 0x2001400
	v_lshl_add_u64 v[54:55], s[30:31], 0, v[54:55]
	v_lshl_add_u64 v[56:57], v[22:23], 0, s[20:21]
	s_mov_b64 s[30:31], 0
	v_mov_b32_e32 v22, v37
	v_mov_b32_e32 v23, v37
	ds_read_b128 v[100:103], v72
	ds_read_b128 v[104:107], v72 offset:16
	ds_read_b128 v[108:111], v72 offset:2048
	ds_read_b128 v[112:115], v72 offset:2064
	ds_read_b128 v[116:119], v72 offset:4096
	ds_read_b128 v[120:123], v72 offset:4112
	ds_read_b128 v[124:127], v72 offset:6144
	ds_read_b128 v[128:131], v72 offset:6160
	ds_read_b128 v[132:135], v72 offset:8192
	ds_read_b128 v[136:139], v72 offset:8208
	ds_read_b128 v[140:143], v72 offset:10240
	ds_read_b128 v[144:147], v72 offset:10256
	s_waitcnt lgkmcnt(0)
	ds_read_b128 v[148:151], v72 offset:12288
	ds_read_b128 v[152:155], v72 offset:12304
	ds_read_b128 v[156:159], v72 offset:14336
	ds_read_b128 v[170:173], v72 offset:14352
	ds_read_b128 v[174:177], v72 offset:16384
	ds_read_b128 v[178:181], v72 offset:16400
	ds_read_b128 v[182:185], v72 offset:18432
	ds_read_b128 v[186:189], v72 offset:18448
	ds_read_b128 v[190:193], v72 offset:20480
	ds_read_b128 v[194:197], v72 offset:20496
	ds_read_b128 v[198:201], v72 offset:22528
	ds_read_b128 v[202:205], v72 offset:22544
	s_waitcnt lgkmcnt(0)
	ds_read_b128 v[206:209], v72 offset:24576
	ds_read_b128 v[210:213], v72 offset:24592
	ds_read_b128 v[226:229], v72 offset:26624
	ds_read_b128 v[230:233], v72 offset:26640
	ds_read_b128 v[234:237], v72 offset:28672
	ds_read_b128 v[238:241], v72 offset:28688
	ds_read_b128 v[242:245], v72 offset:30720
	ds_read_b128 v[246:249], v72 offset:30736
	s_waitcnt lgkmcnt(0)
	s_mov_b32 s52, m0
	s_mov_b32 s62, 0xaaaaaaaa
	s_mov_b32 s63, 0xaaaaaaaa
	s_mov_b32 s64, 0xcccccccc
	s_mov_b32 s65, 0xcccccccc
	s_mov_b32 s66, 0xf0f0f0f0
	s_mov_b32 s67, 0xf0f0f0f0
	s_mov_b64 s[56:57], 0x2000
	s_mov_b64 s[58:59], 16
	s_mov_b64 s[60:61], 0x800
	v_lshrrev_b32_e32 v224, 6, v0
	v_mbcnt_lo_u32_b32 v225, -1, 0
	v_mbcnt_hi_u32_b32 v225, -1, v225
	v_readfirstlane_b32 s50, v224
	v_lshlrev_b32_e32 v224, 4, v225
	s_lshl_b32 s50, s50, 12
	s_add_i32 s50, s50, 0x11000
	s_mov_b32 s53, 0
	v_mov_b32_e32 v160, s53
	v_mov_b32_e32 v161, 0
	v_lshl_add_u64 v[160:161], v[54:55], 0, v[160:161]
	v_lshl_add_u64 v[250:251], v[160:161], 0, s[56:57]
	v_lshl_add_u64 v[252:253], v[160:161], 0, s[34:35]
	v_lshl_add_u64 v[254:255], v[160:161], 0, s[38:39]
	v_lshl_add_u64 v[252:253], v[252:253], 0, s[58:59]
	v_lshl_add_u64 v[254:255], v[254:255], 0, s[58:59]
	v_lshl_add_u64 v[160:161], v[250:251], 0, s[60:61]
	s_mov_b32 m0, s50
	s_nop 0
	global_load_lds_dwordx4 v[250:251], off
	s_add_i32 m0, s50, 0x400
	s_nop 0
	global_load_lds_dwordx4 v[252:253], off
	s_add_i32 m0, s50, 0x800
	s_nop 0
	global_load_lds_dwordx4 v[254:255], off
	s_add_i32 m0, s50, 0xc00
	s_nop 0
	global_load_lds_dwordx4 v[160:161], off
